# weight transposes keep two items (16 KB per wave) in flight: parity-unrolled double buffer, fixed VMEM count per item
# baseline (speedup 1.0000x reference)
; __device__ __forceinline__ int win_dest_row(int n0) {
;     if (n0 < 5120) return n0;
;     if (n0 < 5152) return CDT + (n0 - 5120);
;     if (n0 < 7200) { const int c = n0 - 5152; return CCF + 256 * (c >> 7) + (c & 127); }
;     { const int c = n0 - 7200; return CCF + 256 * (c >> 7) + 128 + (c & 127); }
; }
; __global__ void __launch_bounds__(512, 2) mk_fwd(Args args) {
;     ...
;         for (int it = gw; it < n_items0; it += NGW) {
;             int r = it;
;             if (r < I_IN) { const int nblk = 9248 / 32, kb = r / nblk, nb = r % nblk; p0_transpose_item(w_in, DM, 9248, WinT, 64 * kb, 32 * nb, win_dest_row(32 * nb), scr, lane); continue; } r -= I_IN;
.LBB0_18:
	s_cmp_lt_i32 s88, 1
	s_cselect_b64 s[0:1], -1, 0
	s_cmp_gt_i32 s89, 0
	s_cselect_b64 s[4:5], -1, 0
	s_and_b64 s[0:1], s[0:1], s[4:5]
	s_andn2_b64 vcc, exec, s[0:1]
	s_cbranch_vccnz .LBB0_61
	s_mov_b64 s[8:9], s[96:97]
	v_mov_b32_e32 v1, v212
	s_lshl_b32 s10, s94, 3
	v_readfirstlane_b32 s3, v1
	s_ashr_i32 s4, s3, 6
	s_lshl_b32 s3, s2, 3
	v_and_b32_e32 v3, 63, v1
	s_add_i32 s3, s4, s3
	s_cmpk_gt_i32 s3, 0x382f
	v_lshlrev_b32_e32 v0, 3, v3
	s_cbranch_scc1 .LBB0_54
	s_load_dwordx2 s[12:13], s[8:9], 0x38
	s_load_dwordx2 s[14:15], s[8:9], 0x90
	s_load_dwordx2 s[16:17], s[8:9], 0xa0
	s_load_dwordx2 s[18:19], s[8:9], 0xb8
	s_load_dwordx2 s[20:21], s[8:9], 0x98
	s_load_dwordx2 s[22:23], s[8:9], 0xd0
	v_lshrrev_b32_e32 v4, 3, v3
	v_and_b32_e32 v7, 7, v3
	v_lshlrev_b32_e32 v5, 4, v7
	v_lshlrev_b32_e32 v6, 5, v7
	s_lshl_b32 s24, s4, 14
	v_lshl_add_u32 v16, v4, 7, s24
	v_xor_b32_e32 v8, 0, v7
	v_lshl_add_u32 v8, v8, 4, v16
	v_xor_b32_e32 v9, 1, v7
	v_lshl_add_u32 v9, v9, 4, v16
	v_xor_b32_e32 v10, 2, v7
	v_lshl_add_u32 v10, v10, 4, v16
	v_xor_b32_e32 v11, 3, v7
	v_lshl_add_u32 v11, v11, 4, v16
	v_xor_b32_e32 v12, 4, v7
	v_lshl_add_u32 v12, v12, 4, v16
	v_xor_b32_e32 v13, 5, v7
	v_lshl_add_u32 v13, v13, 4, v16
	v_xor_b32_e32 v14, 6, v7
	v_lshl_add_u32 v14, v14, 4, v16
	v_xor_b32_e32 v15, 7, v7
	v_lshl_add_u32 v15, v15, 4, v16
	v_lshlrev_b32_e32 v20, 2, v7
	v_lshl_add_u32 v21, v7, 10, s24
	v_add_u32_e32 v16, 0, v4
	v_xor_b32_e32 v16, v16, v20
	v_lshl_add_u32 v16, v16, 2, v21
	v_add_u32_e32 v17, 8, v4
	v_xor_b32_e32 v17, v17, v20
	v_lshl_add_u32 v17, v17, 2, v21
	v_add_u32_e32 v18, 16, v4
	v_xor_b32_e32 v18, v18, v20
	v_lshl_add_u32 v18, v18, 2, v21
	v_add_u32_e32 v19, 24, v4
	v_xor_b32_e32 v19, v19, v20
	v_lshl_add_u32 v19, v19, 2, v21
	s_mov_b32 s11, s3
	s_waitcnt lgkmcnt(0)
	s_mov_b32 s53, 0
	s_cmpk_lt_u32 s11, 9248
	s_cbranch_scc0 .Lp0t_pro0_notin
	s_mul_hi_u32 s40, s11, 14861479
	s_mul_i32 s42, s40, 289
	s_sub_u32 s41, s11, s42
	s_mul_i32 s42, s40, 2367488
	s_lshl_b32 s43, s41, 7
	s_add_u32 s42, s42, s43
	s_add_u32 s26, s12, s42
	s_addc_u32 s27, s13, 0
	s_mov_b32 s28, 36992
	s_lshl_b32 s45, s41, 5
	s_mov_b32 s46, s45
	s_cmpk_lt_u32 s45, 5120
	s_cbranch_scc1 .Lp0t_pro0_drow_done
	s_movk_i32 s46, 9216
	s_cmpk_lt_u32 s45, 5152
	s_cbranch_scc1 .Lp0t_pro0_drow_done
	s_sub_u32 s47, s45, 5152
	s_movk_i32 s43, 5120
	s_cmpk_lt_u32 s45, 7200
	s_cbranch_scc1 .Lp0t_pro0_drow_cf
	s_sub_u32 s47, s45, 7200
	s_movk_i32 s43, 5248

; #define LAS __attribute__((address_space(3)))
; __device__ __forceinline__ void p0_transpose_item(const float* W, int K, int N, bf16_t* WT, int k0, int n0, int drow0, LAS float* scr, int lane, const float* kscale = nullptr) {
;     const float ks = kscale ? kscale[k0 + lane] : 1.f;
; #pragma unroll 8
;     for (int i = 0; i < 32; ++i) { const int kk = 2 * i + (lane >> 5); scr[kk * 33 + (lane & 31)] = W[(size_t)(k0 + kk) * N + n0 + (lane & 31)] * __shfl(ks, kk); }
.Lp0t_pro0_decoded:
	v_mad_u32_u24 v20, v4, s28, v5
	s_lshl_b32 s29, s28, 3
	s_and_b32 s42, s40, 31
	s_lshl_b32 s42, s42, 8
	s_add_u32 s34, s20, s42
	s_addc_u32 s35, s21, 0
	global_load_dwordx4 v[32:35], v6, s[34:35]
	global_load_dwordx4 v[36:39], v6, s[34:35] offset:16
	global_load_dwordx4 v[40:43], v20, s[26:27] nt
	s_add_u32 s26, s26, s29
	s_addc_u32 s27, s27, 0
	global_load_dwordx4 v[44:47], v20, s[26:27] nt
	s_add_u32 s26, s26, s29
	s_addc_u32 s27, s27, 0
	global_load_dwordx4 v[48:51], v20, s[26:27] nt
	s_add_u32 s26, s26, s29
	s_addc_u32 s27, s27, 0
	global_load_dwordx4 v[52:55], v20, s[26:27] nt
	s_add_u32 s26, s26, s29
	s_addc_u32 s27, s27, 0
	global_load_dwordx4 v[56:59], v20, s[26:27] nt
	s_add_u32 s26, s26, s29
	s_addc_u32 s27, s27, 0
	global_load_dwordx4 v[60:63], v20, s[26:27] nt
	s_add_u32 s26, s26, s29
	s_addc_u32 s27, s27, 0
	global_load_dwordx4 v[64:67], v20, s[26:27] nt
	s_add_u32 s26, s26, s29
	s_addc_u32 s27, s27, 0
	global_load_dwordx4 v[68:71], v20, s[26:27] nt
	s_add_u32 s11, s11, s10
	s_cmpk_lt_u32 s11, 14384
	s_cbranch_scc0 .Lp0t_pro_single
	s_cmpk_lt_u32 s11, 9248
	s_cbranch_scc0 .Lp0t_pro1_notin
	s_mul_hi_u32 s40, s11, 14861479
	s_mul_i32 s42, s40, 289
	s_sub_u32 s41, s11, s42
	s_mul_i32 s42, s40, 2367488
	s_lshl_b32 s43, s41, 7
	s_add_u32 s42, s42, s43
	s_add_u32 s26, s12, s42
	s_addc_u32 s27, s13, 0
	s_mov_b32 s28, 36992
	s_lshl_b32 s45, s41, 5
	s_mov_b32 s46, s45
	s_cmpk_lt_u32 s45, 5120
	s_cbranch_scc1 .Lp0t_pro1_drow_done
	s_movk_i32 s46, 9216
	s_cmpk_lt_u32 s45, 5152
	s_cbranch_scc1 .Lp0t_pro1_drow_done
	s_sub_u32 s47, s45, 5152
	s_movk_i32 s43, 5120
	s_cmpk_lt_u32 s45, 7200
	s_cbranch_scc1 .Lp0t_pro1_drow_cf
	s_sub_u32 s47, s45, 7200
	s_movk_i32 s43, 5248

; __device__ __forceinline__ int win_dest_row(int n0) {
;     if (n0 < 5120) return n0;
;     if (n0 < 5152) return CDT + (n0 - 5120);
;     if (n0 < 7200) { const int c = n0 - 5152; return CCF + 256 * (c >> 7) + (c & 127); }
;     { const int c = n0 - 7200; return CCF + 256 * (c >> 7) + 128 + (c & 127); }
; __global__ void __launch_bounds__(512, 2) mk_fwd(Args args) {
;     ...
;             if (r < I_IN) { const int nblk = 9248 / 32, kb = r / nblk, nb = r % nblk; p0_transpose_item(w_in, DM, 9248, WinT, 64 * kb, 32 * nb, win_dest_row(32 * nb), scr, lane); continue; } r -= I_IN;
;             if (r < I_OUT) { const int nblk = DM / 32, kb = r / nblk, nb = r % nblk; p0_transpose_item(w_out, DMIX, DM, WoutT, 64 * kb, 32 * nb, 32 * nb, scr, lane); continue; } r -= I_OUT;
;             if (r < I_UP) { const int nblk = FF2 / 32, kb = r / nblk, nb = r % nblk; p0_transpose_item(w_up, DM, FF2, WupT, 64 * kb, 32 * nb, 32 * nb, scr, lane, norm_ffn_w); continue; } r -= I_UP;
.Lp0t_pro1_drow_done:
	s_lshl_b32 s42, s46, 12
	s_lshl_b32 s43, s40, 7
	s_add_u32 s42, s42, s43
	s_add_u32 s48, s22, s42
	s_addc_u32 s49, s23, 0
	s_movk_i32 s50, 4096
	s_mov_b32 s51, 0
	s_branch .Lp0t_pro1_decoded
.Lp0t_pro1_notin:
	s_sub_u32 s44, s11, 9248
	s_cmpk_lt_u32 s44, 4096
	s_cbranch_scc0 .Lp0t_pro1_notout
	s_lshr_b32 s40, s44, 6
	s_and_b32 s41, s44, 63
	s_lshl_b32 s42, s40, 19
	s_lshl_b32 s43, s41, 7
	s_add_u32 s42, s42, s43
	s_add_u32 s26, s14, s42
	s_addc_u32 s27, s15, 0
	s_movk_i32 s28, 8192
	s_lshl_b32 s42, s41, 18
	s_lshl_b32 s43, s40, 7
	s_add_u32 s42, s42, s43
	s_add_u32 s42, s42, 0x2500000
	s_add_u32 s48, s22, s42
	s_addc_u32 s49, s23, 0
	s_movk_i32 s50, 8192
	s_mov_b32 s51, 0
	s_branch .Lp0t_pro1_decoded

; #define LAS __attribute__((address_space(3)))
; __device__ __forceinline__ void p0_transpose_item(const float* W, int K, int N, bf16_t* WT, int k0, int n0, int drow0, LAS float* scr, int lane, const float* kscale = nullptr) {
;     const float ks = kscale ? kscale[k0 + lane] : 1.f;
; #pragma unroll 8
;     for (int i = 0; i < 32; ++i) { const int kk = 2 * i + (lane >> 5); scr[kk * 33 + (lane & 31)] = W[(size_t)(k0 + kk) * N + n0 + (lane & 31)] * __shfl(ks, kk); }
; __global__ void __launch_bounds__(512, 2) mk_fwd(Args args) {
;     ...
;             if (r < I_UP) { const int nblk = FF2 / 32, kb = r / nblk, nb = r % nblk; p0_transpose_item(w_up, DM, FF2, WupT, 64 * kb, 32 * nb, 32 * nb, scr, lane, norm_ffn_w); continue; } r -= I_UP;
;             { const int nblk = DM / 32, kb = r / nblk, nb = r % nblk; p0_transpose_item(w_down, FF, DM, WdnT, 64 * kb, 32 * nb, 32 * nb, scr, lane); }
.Lp0t_pro1_upg:
	s_lshr_b32 s46, s45, 7
	s_lshl_b32 s46, s46, 8
	s_and_b32 s47, s45, 127
	s_add_u32 s46, s46, s47
	s_add_u32 s46, s46, s43
	s_lshl_b32 s42, s46, 12
	s_lshl_b32 s43, s40, 7
	s_add_u32 s42, s42, s43
	s_add_u32 s42, s42, 0x3500000
	s_add_u32 s48, s22, s42
	s_addc_u32 s49, s23, 0
	s_movk_i32 s50, 4096
	s_lshl_b32 s42, s40, 8
	s_add_u32 s34, s20, s42
	s_addc_u32 s35, s21, 0
	s_mov_b32 s51, 1
	s_branch .Lp0t_pro1_decoded
.Lp0t_pro1_notup:
	s_sub_u32 s44, s44, 11008
	s_lshr_b32 s40, s44, 6
	s_and_b32 s41, s44, 63
	s_lshl_b32 s42, s40, 19
	s_lshl_b32 s43, s41, 7
	s_add_u32 s42, s42, s43
	s_add_u32 s26, s18, s42
	s_addc_u32 s27, s19, 0
	s_movk_i32 s28, 8192
	s_mul_i32 s42, s41, 352256
	s_lshl_b32 s43, s40, 7
	s_add_u32 s42, s42, s43
	s_add_u32 s42, s42, 0x6000000
	s_add_u32 s48, s22, s42
	s_addc_u32 s49, s23, 0
	s_movk_i32 s50, 11008
	s_mov_b32 s51, 0
.Lp0t_pro1_decoded:
	v_mad_u32_u24 v20, v4, s28, v5
	s_lshl_b32 s29, s28, 3
	s_and_b32 s42, s40, 31
	s_lshl_b32 s42, s42, 8
	s_add_u32 s34, s20, s42
	s_addc_u32 s35, s21, 0
	global_load_dwordx4 v[136:139], v6, s[34:35]
	global_load_dwordx4 v[140:143], v6, s[34:35] offset:16
	global_load_dwordx4 v[104:107], v20, s[26:27] nt
	s_add_u32 s26, s26, s29
	s_addc_u32 s27, s27, 0
	global_load_dwordx4 v[108:111], v20, s[26:27] nt
	s_add_u32 s26, s26, s29
	s_addc_u32 s27, s27, 0
	global_load_dwordx4 v[112:115], v20, s[26:27] nt
	s_add_u32 s26, s26, s29
	s_addc_u32 s27, s27, 0
	global_load_dwordx4 v[116:119], v20, s[26:27] nt
	s_add_u32 s26, s26, s29
	s_addc_u32 s27, s27, 0
	global_load_dwordx4 v[120:123], v20, s[26:27] nt
	s_add_u32 s26, s26, s29
	s_addc_u32 s27, s27, 0
	global_load_dwordx4 v[124:127], v20, s[26:27] nt
	s_add_u32 s26, s26, s29
	s_addc_u32 s27, s27, 0
	global_load_dwordx4 v[128:131], v20, s[26:27] nt
	s_add_u32 s26, s26, s29
	s_addc_u32 s27, s27, 0
	global_load_dwordx4 v[132:135], v20, s[26:27] nt
	s_mov_b32 s53, 1
	s_add_u32 s11, s11, s10
	s_waitcnt vmcnt(10)
	s_branch .Lp0t_pro_stage

; #define LAS __attribute__((address_space(3)))
; __device__ __forceinline__ unsigned pk2(float lo, float hi) { unsigned r; asm("v_cvt_pk_bf16_f32 %0, %1, %2" : "=v"(r) : "v"(lo), "v"(hi)); return r; }
; __device__ __forceinline__ void p0_transpose_item(const float* W, int K, int N, bf16_t* WT, int k0, int n0, int drow0, LAS float* scr, int lane, const float* kscale = nullptr) {
;     const float ks = kscale ? kscale[k0 + lane] : 1.f;
; #pragma unroll 8
;     for (int i = 0; i < 32; ++i) { const int kk = 2 * i + (lane >> 5); scr[kk * 33 + (lane & 31)] = W[(size_t)(k0 + kk) * N + n0 + (lane & 31)] * __shfl(ks, kk); }
;     asm volatile("s_waitcnt lgkmcnt(0)" ::: "memory");
;     const int c = lane & 7;
; #pragma unroll
;     for (int j = 0; j < 4; ++j) { const int n = (lane >> 3) + 8 * j; const LAS float* s = scr + (8 * c) * 33 + n;
;         u32x4 o; o.x = pk2(s[0 * 33], s[1 * 33]); o.y = pk2(s[2 * 33], s[3 * 33]); o.z = pk2(s[4 * 33], s[5 * 33]); o.w = pk2(s[6 * 33], s[7 * 33]);
;         *(u32x4*)(WT + (size_t)(drow0 + n) * K + k0 + 8 * c) = o; }
;     asm volatile("s_waitcnt lgkmcnt(0)" ::: "memory");
.Lp0t_pro_stage:
	ds_write_b128 v8, v[40:43] offset:0
	ds_write_b128 v9, v[44:47] offset:1024
	ds_write_b128 v10, v[48:51] offset:2048
	ds_write_b128 v11, v[52:55] offset:3072
	ds_write_b128 v12, v[56:59] offset:4096
	ds_write_b128 v13, v[60:63] offset:5120
	ds_write_b128 v14, v[64:67] offset:6144
	ds_write_b128 v15, v[68:71] offset:7168
	v_mov_b32_e32 v24, v32
	v_mov_b32_e32 v25, v33
	v_mov_b32_e32 v26, v34
	v_mov_b32_e32 v27, v35
	v_mov_b32_e32 v28, v36
	v_mov_b32_e32 v29, v37
	v_mov_b32_e32 v30, v38
	v_mov_b32_e32 v31, v39
	s_mov_b64 s[36:37], s[30:31]
	s_mov_b32 s38, s32
	s_mov_b32 s52, s33
	s_waitcnt lgkmcnt(0)
.Lp0t_body0:
	s_mov_b32 s54, 0
	s_cmp_eq_u32 s53, 0
	s_cbranch_scc1 .Lp0t_noload0
	s_cmpk_lt_u32 s11, 14384
	s_cbranch_scc0 .Lp0t_noload0
	s_cmpk_lt_u32 s11, 9248
	s_cbranch_scc0 .Lp0t_m0_notin
	s_mul_hi_u32 s40, s11, 14861479
	s_mul_i32 s42, s40, 289
	s_sub_u32 s41, s11, s42
	s_mul_i32 s42, s40, 2367488
	s_lshl_b32 s43, s41, 7
	s_add_u32 s42, s42, s43
	s_add_u32 s26, s12, s42
	s_addc_u32 s27, s13, 0
	s_mov_b32 s28, 36992
	s_lshl_b32 s45, s41, 5
	s_mov_b32 s46, s45
	s_cmpk_lt_u32 s45, 5120
	s_cbranch_scc1 .Lp0t_m0_drow_done
	s_movk_i32 s46, 9216
	s_cmpk_lt_u32 s45, 5152
	s_cbranch_scc1 .Lp0t_m0_drow_done
	s_sub_u32 s47, s45, 5152
	s_movk_i32 s43, 5120
	s_cmpk_lt_u32 s45, 7200
	s_cbranch_scc1 .Lp0t_m0_drow_cf
	s_sub_u32 s47, s45, 7200
	s_movk_i32 s43, 5248

; #define LAS __attribute__((address_space(3)))
; __device__ __forceinline__ unsigned pk2(float lo, float hi) { unsigned r; asm("v_cvt_pk_bf16_f32 %0, %1, %2" : "=v"(r) : "v"(lo), "v"(hi)); return r; }
; __device__ __forceinline__ void p0_transpose_item(const float* W, int K, int N, bf16_t* WT, int k0, int n0, int drow0, LAS float* scr, int lane, const float* kscale = nullptr) {
;     ...
;     const int c = lane & 7;
; #pragma unroll
;     for (int j = 0; j < 4; ++j) { const int n = (lane >> 3) + 8 * j; const LAS float* s = scr + (8 * c) * 33 + n;
;         u32x4 o; o.x = pk2(s[0 * 33], s[1 * 33]); o.y = pk2(s[2 * 33], s[3 * 33]); o.z = pk2(s[4 * 33], s[5 * 33]); o.w = pk2(s[6 * 33], s[7 * 33]);
;         *(u32x4*)(WT + (size_t)(drow0 + n) * K + k0 + 8 * c) = o; }
;     asm volatile("s_waitcnt lgkmcnt(0)" ::: "memory");
.Lp0t_m0_decoded:
	v_mad_u32_u24 v20, v4, s28, v5
	s_lshl_b32 s29, s28, 3
	s_and_b32 s42, s40, 31
	s_lshl_b32 s42, s42, 8
	s_add_u32 s34, s20, s42
	s_addc_u32 s35, s21, 0
	global_load_dwordx4 v[32:35], v6, s[34:35]
	global_load_dwordx4 v[36:39], v6, s[34:35] offset:16
	global_load_dwordx4 v[40:43], v20, s[26:27] nt
	s_add_u32 s26, s26, s29
	s_addc_u32 s27, s27, 0
	global_load_dwordx4 v[44:47], v20, s[26:27] nt
	s_add_u32 s26, s26, s29
	s_addc_u32 s27, s27, 0
	global_load_dwordx4 v[48:51], v20, s[26:27] nt
	s_add_u32 s26, s26, s29
	s_addc_u32 s27, s27, 0
	global_load_dwordx4 v[52:55], v20, s[26:27] nt
	s_add_u32 s26, s26, s29
	s_addc_u32 s27, s27, 0
	global_load_dwordx4 v[56:59], v20, s[26:27] nt
	s_add_u32 s26, s26, s29
	s_addc_u32 s27, s27, 0
	global_load_dwordx4 v[60:63], v20, s[26:27] nt
	s_add_u32 s26, s26, s29
	s_addc_u32 s27, s27, 0
	global_load_dwordx4 v[64:67], v20, s[26:27] nt
	s_add_u32 s26, s26, s29
	s_addc_u32 s27, s27, 0
	global_load_dwordx4 v[68:71], v20, s[26:27] nt
	s_mov_b32 s54, 1
	s_add_u32 s11, s11, s10
.Lp0t_noload0:
	ds_read2_b32 v[72:73], v16 offset0:0 offset1:32
	ds_read2_b32 v[74:75], v16 offset0:64 offset1:96
	ds_read2_b32 v[76:77], v16 offset0:128 offset1:160
	ds_read2_b32 v[78:79], v16 offset0:192 offset1:224
	ds_read2_b32 v[80:81], v17 offset0:0 offset1:32
	ds_read2_b32 v[82:83], v17 offset0:64 offset1:96
	ds_read2_b32 v[84:85], v17 offset0:128 offset1:160
	ds_read2_b32 v[86:87], v17 offset0:192 offset1:224
	ds_read2_b32 v[88:89], v18 offset0:0 offset1:32
	ds_read2_b32 v[90:91], v18 offset0:64 offset1:96
	ds_read2_b32 v[92:93], v18 offset0:128 offset1:160
	ds_read2_b32 v[94:95], v18 offset0:192 offset1:224
	v_mad_u32_u24 v21, v4, s38, v5
	s_lshl_b32 s39, s38, 3
	s_waitcnt lgkmcnt(8)
	ds_read2_b32 v[96:97], v19 offset0:0 offset1:32
	ds_read2_b32 v[98:99], v19 offset0:64 offset1:96
	ds_read2_b32 v[100:101], v19 offset0:128 offset1:160
	ds_read2_b32 v[102:103], v19 offset0:192 offset1:224
	s_cmp_eq_u32 s52, 0
	s_cbranch_scc1 .Lpc_nomul_1
	v_mul_f32_e32 v72, v72, v24
	v_mul_f32_e32 v73, v73, v25
	v_mul_f32_e32 v74, v74, v26
	v_mul_f32_e32 v75, v75, v27
	v_mul_f32_e32 v76, v76, v28
	v_mul_f32_e32 v77, v77, v29
	v_mul_f32_e32 v78, v78, v30
	v_mul_f32_e32 v79, v79, v31
.Lpc_nomul_1:
	v_cvt_pk_bf16_f32 v72, v72, v73
	v_cvt_pk_bf16_f32 v73, v74, v75
	v_cvt_pk_bf16_f32 v74, v76, v77
	v_cvt_pk_bf16_f32 v75, v78, v79
	global_store_dwordx4 v21, v[72:75], s[36:37]
	s_add_u32 s36, s36, s39
	s_addc_u32 s37, s37, 0
	s_waitcnt lgkmcnt(8)
	s_cmp_eq_u32 s52, 0
	s_cbranch_scc1 .Lpc_nomul_2
	v_mul_f32_e32 v80, v80, v24
	v_mul_f32_e32 v81, v81, v25
	v_mul_f32_e32 v82, v82, v26
	v_mul_f32_e32 v83, v83, v27
	v_mul_f32_e32 v84, v84, v28
	v_mul_f32_e32 v85, v85, v29
	v_mul_f32_e32 v86, v86, v30
	v_mul_f32_e32 v87, v87, v31
.Lpc_nomul_2:
	v_cvt_pk_bf16_f32 v80, v80, v81
	v_cvt_pk_bf16_f32 v81, v82, v83
	v_cvt_pk_bf16_f32 v82, v84, v85
	v_cvt_pk_bf16_f32 v83, v86, v87
	global_store_dwordx4 v21, v[80:83], s[36:37]
	s_add_u32 s36, s36, s39
	s_addc_u32 s37, s37, 0
	s_waitcnt lgkmcnt(4)
	s_cmp_eq_u32 s52, 0
	s_cbranch_scc1 .Lpc_nomul_3
	v_mul_f32_e32 v88, v88, v24
	v_mul_f32_e32 v89, v89, v25
	v_mul_f32_e32 v90, v90, v26
	v_mul_f32_e32 v91, v91, v27
	v_mul_f32_e32 v92, v92, v28
	v_mul_f32_e32 v93, v93, v29
	v_mul_f32_e32 v94, v94, v30
	v_mul_f32_e32 v95, v95, v31
.Lpc_nomul_3:
	v_cvt_pk_bf16_f32 v88, v88, v89
	v_cvt_pk_bf16_f32 v89, v90, v91
	v_cvt_pk_bf16_f32 v90, v92, v93
	v_cvt_pk_bf16_f32 v91, v94, v95
	global_store_dwordx4 v21, v[88:91], s[36:37]
	s_add_u32 s36, s36, s39
	s_addc_u32 s37, s37, 0
	s_waitcnt lgkmcnt(0)
	s_cmp_eq_u32 s52, 0
	s_cbranch_scc1 .Lpc_nomul_4
	v_mul_f32_e32 v96, v96, v24
	v_mul_f32_e32 v97, v97, v25
	v_mul_f32_e32 v98, v98, v26
	v_mul_f32_e32 v99, v99, v27
	v_mul_f32_e32 v100, v100, v28
	v_mul_f32_e32 v101, v101, v29
	v_mul_f32_e32 v102, v102, v30
	v_mul_f32_e32 v103, v103, v31
.Lpc_nomul_4:
	v_cvt_pk_bf16_f32 v96, v96, v97
	v_cvt_pk_bf16_f32 v97, v98, v99
	v_cvt_pk_bf16_f32 v98, v100, v101
	v_cvt_pk_bf16_f32 v99, v102, v103
	global_store_dwordx4 v21, v[96:99], s[36:37]
	s_cmp_eq_u32 s53, 0
	s_cbranch_scc1 .Lp0t_done
	s_cmp_eq_u32 s54, 0
	s_cbranch_scc1 .Lp0t_w4_0
	s_waitcnt vmcnt(14)
	s_branch .Lp0t_wd_0
.Lp0t_w4_0:
	s_waitcnt vmcnt(4)
.Lp0t_wd_0:
	ds_write_b128 v8, v[104:107] offset:0
	ds_write_b128 v9, v[108:111] offset:1024
	ds_write_b128 v10, v[112:115] offset:2048
	ds_write_b128 v11, v[116:119] offset:3072
	ds_write_b128 v12, v[120:123] offset:4096
	ds_write_b128 v13, v[124:127] offset:5120
	ds_write_b128 v14, v[128:131] offset:6144
	ds_write_b128 v15, v[132:135] offset:7168
	v_mov_b32_e32 v24, v136
	v_mov_b32_e32 v25, v137
	v_mov_b32_e32 v26, v138
	v_mov_b32_e32 v27, v139
	v_mov_b32_e32 v28, v140
	v_mov_b32_e32 v29, v141
	v_mov_b32_e32 v30, v142
	v_mov_b32_e32 v31, v143
	s_mov_b64 s[36:37], s[48:49]
	s_mov_b32 s38, s50
	s_mov_b32 s52, s51
	s_waitcnt lgkmcnt(0)
	s_mov_b32 s53, s54

; #define LAS __attribute__((address_space(3)))
; __device__ __forceinline__ void p0_transpose_item(const float* W, int K, int N, bf16_t* WT, int k0, int n0, int drow0, LAS float* scr, int lane, const float* kscale = nullptr) {
;     const float ks = kscale ? kscale[k0 + lane] : 1.f;
; #pragma unroll 8
;     for (int i = 0; i < 32; ++i) { const int kk = 2 * i + (lane >> 5); scr[kk * 33 + (lane & 31)] = W[(size_t)(k0 + kk) * N + n0 + (lane & 31)] * __shfl(ks, kk); }
.Lp0t_m1_decoded:
	v_mad_u32_u24 v20, v4, s28, v5
	s_lshl_b32 s29, s28, 3
	s_and_b32 s42, s40, 31
	s_lshl_b32 s42, s42, 8
	s_add_u32 s34, s20, s42
	s_addc_u32 s35, s21, 0
	global_load_dwordx4 v[136:139], v6, s[34:35]
	global_load_dwordx4 v[140:143], v6, s[34:35] offset:16
	global_load_dwordx4 v[104:107], v20, s[26:27] nt
	s_add_u32 s26, s26, s29
	s_addc_u32 s27, s27, 0
	global_load_dwordx4 v[108:111], v20, s[26:27] nt
	s_add_u32 s26, s26, s29
	s_addc_u32 s27, s27, 0
	global_load_dwordx4 v[112:115], v20, s[26:27] nt
	s_add_u32 s26, s26, s29
	s_addc_u32 s27, s27, 0
	global_load_dwordx4 v[116:119], v20, s[26:27] nt
	s_add_u32 s26, s26, s29
	s_addc_u32 s27, s27, 0
	global_load_dwordx4 v[120:123], v20, s[26:27] nt
	s_add_u32 s26, s26, s29
	s_addc_u32 s27, s27, 0
	global_load_dwordx4 v[124:127], v20, s[26:27] nt
	s_add_u32 s26, s26, s29
	s_addc_u32 s27, s27, 0
	global_load_dwordx4 v[128:131], v20, s[26:27] nt
	s_add_u32 s26, s26, s29
	s_addc_u32 s27, s27, 0
	global_load_dwordx4 v[132:135], v20, s[26:27] nt
	s_mov_b32 s54, 1
	s_add_u32 s11, s11, s10

; __device__ __forceinline__ void rms_row_to_bf16(const float* xrow, const float* w, bf16_t* orow, int lane) {
;     f32x4 v[8], ww[8]; float s = 0.f;
; #pragma unroll
;     for (int j = 0; j < 8; ++j) { v[j] = *(const f32x4*)(xrow + (j * 64 + lane) * 4); ww[j] = *(const f32x4*)(w + (j * 64 + lane) * 4); }
; #pragma unroll
; __global__ void __launch_bounds__(512, 2) mk_fwd(Args args) {
;     ...
;         const int gr = (gw + NGW - (n_items0 % NGW)) % NGW;
;         for (int m = gr; m < MT; m += NGW) { const float* xr = (m < MP) ? x_prompt + (size_t)m * DM : x_sample + (size_t)(m - MP) * DM; rms_row_to_bf16(xr, norm_mix_w, XN + (size_t)m * DM, lane); }
.Lp0t_wd_1:
	ds_write_b128 v8, v[40:43] offset:0
	ds_write_b128 v9, v[44:47] offset:1024
	ds_write_b128 v10, v[48:51] offset:2048
	ds_write_b128 v11, v[52:55] offset:3072
	ds_write_b128 v12, v[56:59] offset:4096
	ds_write_b128 v13, v[60:63] offset:5120
	ds_write_b128 v14, v[64:67] offset:6144
	ds_write_b128 v15, v[68:71] offset:7168
	v_mov_b32_e32 v24, v32
	v_mov_b32_e32 v25, v33
	v_mov_b32_e32 v26, v34
	v_mov_b32_e32 v27, v35
	v_mov_b32_e32 v28, v36
	v_mov_b32_e32 v29, v37
	v_mov_b32_e32 v30, v38
	v_mov_b32_e32 v31, v39
	s_mov_b64 s[36:37], s[30:31]
	s_mov_b32 s38, s32
	s_mov_b32 s52, s33
	s_waitcnt lgkmcnt(0)
	s_mov_b32 s53, s54
	s_branch .Lp0t_body0
.Lp0t_done:
.LBB0_54:
	s_abs_i32 s4, s10
	v_cvt_f32_u32_e32 v1, s4
	s_sub_i32 s5, 0, s4
	s_add_i32 s3, s3, s10
	v_rcp_iflag_f32_e32 v1, v1
	s_nop 0
	v_mul_f32_e32 v1, 0x4f7ffffe, v1
	v_cvt_u32_f32_e32 v1, v1
	s_nop 0
	v_readfirstlane_b32 s6, v1
	s_mul_i32 s5, s5, s6
	s_mul_hi_u32 s5, s6, s5
	s_add_i32 s6, s6, s5
	s_mul_hi_u32 s5, s6, 0x3830
	s_mul_i32 s5, s5, s4
	s_sub_i32 s5, 0x3830, s5
	s_sub_i32 s7, s5, s4
	s_cmp_ge_u32 s5, s4
	s_cselect_b32 s5, s7, s5
	s_sub_i32 s7, s5, s4
	s_cmp_ge_u32 s5, s4
	s_cselect_b32 s5, s7, s5
	s_sub_i32 s3, s3, s5
	s_ashr_i32 s5, s3, 31
	s_abs_i32 s3, s3
	s_mul_hi_u32 s6, s3, s6
	s_mul_i32 s6, s6, s4
	s_sub_i32 s3, s3, s6
	s_sub_i32 s6, s3, s4
	s_cmp_ge_u32 s3, s4
	s_cselect_b32 s3, s6, s3
	s_sub_i32 s6, s3, s4
	s_cmp_ge_u32 s3, s4
	s_cselect_b32 s3, s6, s3
	s_xor_b32 s3, s3, s5
	s_sub_i32 s4, s3, s5
	s_cmpk_gt_i32 s4, 0x21ff
	s_mov_b32 s7, 0
	s_cbranch_scc1 .LBB0_61
	s_load_dwordx2 s[12:13], s[8:9], 0x0
	s_load_dwordx2 s[14:15], s[8:9], 0x8
	s_load_dwordx2 s[16:17], s[8:9], 0x30
	s_load_dwordx2 s[18:19], s[8:9], 0xd0
	v_lshlrev_b32_e32 v4, 4, v3
	v_lshlrev_b32_e32 v5, 3, v3
	v_xor_b32_e32 v6, 1, v3
	v_lshlrev_b32_e32 v6, 2, v6
	v_xor_b32_e32 v7, 2, v3
	v_lshlrev_b32_e32 v7, 2, v7
	v_xor_b32_e32 v8, 4, v3
	v_lshlrev_b32_e32 v8, 2, v8
	v_xor_b32_e32 v9, 8, v3
	v_lshlrev_b32_e32 v9, 2, v9
	v_xor_b32_e32 v10, 16, v3
	v_lshlrev_b32_e32 v10, 2, v10
	v_xor_b32_e32 v11, 32, v3
	v_lshlrev_b32_e32 v11, 2, v11
	v_mov_b32_e32 v16, 0x3727c5ac
	s_waitcnt lgkmcnt(0)
	s_add_u32 s18, s18, 0x7580000
	s_addc_u32 s19, s19, 0
	global_load_dwordx4 v[40:43], v4, s[16:17] offset:0
	global_load_dwordx4 v[44:47], v4, s[16:17] offset:1024
	global_load_dwordx4 v[48:51], v4, s[16:17] offset:2048
	global_load_dwordx4 v[52:55], v4, s[16:17] offset:3072
	s_add_u32 s16, s16, 4096
	s_addc_u32 s17, s17, 0
	global_load_dwordx4 v[56:59], v4, s[16:17] offset:0
	global_load_dwordx4 v[60:63], v4, s[16:17] offset:1024
	global_load_dwordx4 v[64:67], v4, s[16:17] offset:2048
	global_load_dwordx4 v[68:71], v4, s[16:17] offset:3072
	s_cmpk_lt_u32 s4, 8192
	s_cselect_b32 s20, s12, s14
	s_cselect_b32 s21, s13, s15
	s_cselect_b32 s28, 0, 8192
	s_sub_u32 s28, s4, s28
	s_lshr_b32 s29, s28, 19
	s_lshl_b32 s28, s28, 13
	s_add_u32 s20, s20, s28
	s_addc_u32 s21, s21, s29
	global_load_dwordx4 v[72:75], v4, s[20:21] offset:0 nt
	global_load_dwordx4 v[76:79], v4, s[20:21] offset:1024 nt
	global_load_dwordx4 v[80:83], v4, s[20:21] offset:2048 nt
	global_load_dwordx4 v[84:87], v4, s[20:21] offset:3072 nt
	s_add_u32 s20, s20, 4096
	s_addc_u32 s21, s21, 0
	global_load_dwordx4 v[88:91], v4, s[20:21] offset:0 nt
	global_load_dwordx4 v[92:95], v4, s[20:21] offset:1024 nt
	global_load_dwordx4 v[96:99], v4, s[20:21] offset:2048 nt
	global_load_dwordx4 v[100:103], v4, s[20:21] offset:3072 nt
	s_mov_b32 s27, 0

; #define LAS __attribute__((address_space(3)))
; __device__ __forceinline__ int ltid() { int t = threadIdx.x; asm volatile("" : "+v"(t)); return t; }
; __device__ __forceinline__ KArgs ka_get() { KArgs p = (KArgs)__builtin_amdgcn_kernarg_segment_ptr(); asm volatile("" : "+s"(p)); return p; }
; __global__ void __launch_bounds__(512, 2) mk_fwd(Args args) {
;     ...
;     if (IN(0)) { const KArgs KA = ka_get(); const int tid = ltid(), lane = tid & 63, wave = __builtin_amdgcn_readfirstlane(tid >> 6); (void)lane; (void)wave;
;         LAS float* scr = (LAS float*)(lds + wave * 16384);
;         const int gw = bx * 8 + wave, NGW = G * 8;
;         constexpr int I_IN = (DM / 64) * (9248 / 32), I_OUT = (DMIX / 64) * (DM / 32), I_UP = (DM / 64) * (FF2 / 32), I_DN = (FF / 64) * (DM / 32);
;         constexpr int n_items0 = I_IN + I_OUT + I_UP + I_DN;
;         for (int it = gw; it < n_items0; it += NGW) {
;             int r = it;
;             if (r < I_IN) { const int nblk = 9248 / 32, kb = r / nblk, nb = r % nblk; p0_transpose_item(w_in, DM, 9248, WinT, 64 * kb, 32 * nb, win_dest_row(32 * nb), scr, lane); continue; } r -= I_IN;
.LBB0_153:
	v_writelane_b32 v254, s3, 0
	v_writelane_b32 v254, s4, 1
	v_writelane_b32 v254, s8, 2
	v_writelane_b32 v254, s9, 3
	v_writelane_b32 v254, s10, 4
	v_writelane_b32 v254, s11, 5
	v_writelane_b32 v254, s12, 6
	v_writelane_b32 v254, s13, 7
	v_writelane_b32 v254, s14, 8
	v_writelane_b32 v254, s15, 9
	v_writelane_b32 v254, s16, 10
	v_writelane_b32 v254, s17, 11
	v_writelane_b32 v254, s18, 12
	v_writelane_b32 v254, s19, 13
	v_writelane_b32 v254, s20, 14
	v_writelane_b32 v254, s21, 15
	v_writelane_b32 v254, s22, 16
	v_writelane_b32 v254, s23, 17
	v_writelane_b32 v254, s24, 18
	v_writelane_b32 v254, s25, 19
	v_writelane_b32 v254, s26, 20
	v_writelane_b32 v254, s27, 21
	v_writelane_b32 v254, s28, 22
	v_writelane_b32 v254, s29, 23
	v_writelane_b32 v254, s30, 24
	v_writelane_b32 v254, s31, 25
	v_writelane_b32 v254, s32, 26
	v_writelane_b32 v254, s33, 27
	v_writelane_b32 v254, s34, 28
	v_writelane_b32 v254, s35, 29
	v_writelane_b32 v254, s36, 30
	v_writelane_b32 v254, s37, 31
	v_writelane_b32 v254, s38, 32
	v_writelane_b32 v254, s39, 33
	v_writelane_b32 v254, s40, 34
	v_writelane_b32 v254, s41, 35
	v_writelane_b32 v254, s42, 36
	v_writelane_b32 v254, s43, 37
	v_writelane_b32 v254, s44, 38
	v_writelane_b32 v254, s45, 39
	v_writelane_b32 v254, s46, 40
	v_writelane_b32 v254, s47, 41
	v_writelane_b32 v254, s48, 42
	v_writelane_b32 v254, s49, 43
	v_writelane_b32 v254, s50, 44
	v_writelane_b32 v254, s51, 45
	v_writelane_b32 v254, s52, 46
	v_writelane_b32 v254, s53, 47
	v_writelane_b32 v254, s54, 48
	v_writelane_b32 v254, s55, 49
	s_cmpk_lt_u32 s2, 234
	s_cbranch_scc1 .Ltup1_skip
	s_mov_b64 s[8:9], s[96:97]
	v_and_b32_e32 v3, 63, v212
	v_readfirstlane_b32 s4, v212
	s_sub_u32 s3, s2, 234
	s_lshl_b32 s3, s3, 3
	s_lshr_b32 s4, s4, 6
	s_add_u32 s3, s3, s4
	s_add_u32 s11, s3, 17456
	s_sub_u32 s10, s94, 234
	s_lshl_b32 s10, s10, 3
	s_cmpk_lt_u32 s11, 20256
	s_cbranch_scc0 .Ltup1_skip
	s_load_dwordx2 s[12:13], s[8:9], 0x38
	s_load_dwordx2 s[14:15], s[8:9], 0x90
	s_load_dwordx2 s[16:17], s[8:9], 0xa0
	s_load_dwordx2 s[18:19], s[8:9], 0xb8
	s_load_dwordx2 s[20:21], s[8:9], 0x98
	s_load_dwordx2 s[22:23], s[8:9], 0xd0
	v_lshrrev_b32_e32 v4, 3, v3
	v_and_b32_e32 v7, 7, v3
	v_lshlrev_b32_e32 v5, 4, v7
	v_lshlrev_b32_e32 v6, 5, v7
	s_lshl_b32 s24, s4, 14
	v_lshl_add_u32 v16, v4, 7, s24
	v_xor_b32_e32 v8, 0, v7
	v_lshl_add_u32 v8, v8, 4, v16
	v_xor_b32_e32 v9, 1, v7
	v_lshl_add_u32 v9, v9, 4, v16
	v_xor_b32_e32 v10, 2, v7
	v_lshl_add_u32 v10, v10, 4, v16
	v_xor_b32_e32 v11, 3, v7
	v_lshl_add_u32 v11, v11, 4, v16
	v_xor_b32_e32 v12, 4, v7
	v_lshl_add_u32 v12, v12, 4, v16
	v_xor_b32_e32 v13, 5, v7
	v_lshl_add_u32 v13, v13, 4, v16
	v_xor_b32_e32 v14, 6, v7
	v_lshl_add_u32 v14, v14, 4, v16
	v_xor_b32_e32 v15, 7, v7
	v_lshl_add_u32 v15, v15, 4, v16
	v_lshlrev_b32_e32 v20, 2, v7
	v_lshl_add_u32 v21, v7, 10, s24
	v_add_u32_e32 v16, 0, v4
	v_xor_b32_e32 v16, v16, v20
	v_lshl_add_u32 v16, v16, 2, v21
	v_add_u32_e32 v17, 8, v4
	v_xor_b32_e32 v17, v17, v20
	v_lshl_add_u32 v17, v17, 2, v21
	v_add_u32_e32 v18, 16, v4
	v_xor_b32_e32 v18, v18, v20
	v_lshl_add_u32 v18, v18, 2, v21
	v_add_u32_e32 v19, 24, v4
	v_xor_b32_e32 v19, v19, v20
	v_lshl_add_u32 v19, v19, 2, v21
	s_waitcnt lgkmcnt(0)
	s_mov_b32 s53, 0
	s_cmpk_lt_u32 s11, 9248
	s_cbranch_scc0 .Ltup1_pro0_notin
	s_mul_hi_u32 s40, s11, 14861479
	s_mul_i32 s42, s40, 289
	s_sub_u32 s41, s11, s42
	s_mul_i32 s42, s40, 2367488
	s_lshl_b32 s43, s41, 7
	s_add_u32 s42, s42, s43
	s_add_u32 s26, s12, s42
	s_addc_u32 s27, s13, 0
	s_mov_b32 s28, 36992
	s_lshl_b32 s45, s41, 5
	s_mov_b32 s46, s45
	s_cmpk_lt_u32 s45, 5120
	s_cbranch_scc1 .Ltup1_pro0_drow_done
	s_movk_i32 s46, 9216
	s_cmpk_lt_u32 s45, 5152
	s_cbranch_scc1 .Ltup1_pro0_drow_done
	s_sub_u32 s47, s45, 5152
	s_movk_i32 s43, 5120
	s_cmpk_lt_u32 s45, 7200
	s_cbranch_scc1 .Ltup1_pro0_drow_cf
	s_sub_u32 s47, s45, 7200
	s_movk_i32 s43, 5248

; #define LAS __attribute__((address_space(3)))
; __device__ __forceinline__ void p0_transpose_item(const float* W, int K, int N, bf16_t* WT, int k0, int n0, int drow0, LAS float* scr, int lane, const float* kscale = nullptr) {
;     const float ks = kscale ? kscale[k0 + lane] : 1.f;
; #pragma unroll 8
;     for (int i = 0; i < 32; ++i) { const int kk = 2 * i + (lane >> 5); scr[kk * 33 + (lane & 31)] = W[(size_t)(k0 + kk) * N + n0 + (lane & 31)] * __shfl(ks, kk); }
.Ltup1_pro0_decoded:
	v_mad_u32_u24 v20, v4, s28, v5
	s_lshl_b32 s29, s28, 3
	s_and_b32 s42, s40, 31
	s_lshl_b32 s42, s42, 8
	s_add_u32 s34, s20, s42
	s_addc_u32 s35, s21, 0
	global_load_dwordx4 v[32:35], v6, s[34:35]
	global_load_dwordx4 v[36:39], v6, s[34:35] offset:16
	global_load_dwordx4 v[40:43], v20, s[26:27] nt
	s_add_u32 s26, s26, s29
	s_addc_u32 s27, s27, 0
	global_load_dwordx4 v[44:47], v20, s[26:27] nt
	s_add_u32 s26, s26, s29
	s_addc_u32 s27, s27, 0
	global_load_dwordx4 v[48:51], v20, s[26:27] nt
	s_add_u32 s26, s26, s29
	s_addc_u32 s27, s27, 0
	global_load_dwordx4 v[52:55], v20, s[26:27] nt
	s_add_u32 s26, s26, s29
	s_addc_u32 s27, s27, 0
	global_load_dwordx4 v[56:59], v20, s[26:27] nt
	s_add_u32 s26, s26, s29
	s_addc_u32 s27, s27, 0
	global_load_dwordx4 v[60:63], v20, s[26:27] nt
	s_add_u32 s26, s26, s29
	s_addc_u32 s27, s27, 0
	global_load_dwordx4 v[64:67], v20, s[26:27] nt
	s_add_u32 s26, s26, s29
	s_addc_u32 s27, s27, 0
	global_load_dwordx4 v[68:71], v20, s[26:27] nt
	s_add_u32 s11, s11, s10
	s_cmpk_lt_u32 s11, 20256
	s_cbranch_scc0 .Ltup1_pro_single
	s_cmpk_lt_u32 s11, 9248
	s_cbranch_scc0 .Ltup1_pro1_notin
	s_mul_hi_u32 s40, s11, 14861479
	s_mul_i32 s42, s40, 289
	s_sub_u32 s41, s11, s42
	s_mul_i32 s42, s40, 2367488
	s_lshl_b32 s43, s41, 7
	s_add_u32 s42, s42, s43
	s_add_u32 s26, s12, s42
	s_addc_u32 s27, s13, 0
	s_mov_b32 s28, 36992
	s_lshl_b32 s45, s41, 5
	s_mov_b32 s46, s45
	s_cmpk_lt_u32 s45, 5120
	s_cbranch_scc1 .Ltup1_pro1_drow_done
	s_movk_i32 s46, 9216
	s_cmpk_lt_u32 s45, 5152
	s_cbranch_scc1 .Ltup1_pro1_drow_done
	s_sub_u32 s47, s45, 5152
	s_movk_i32 s43, 5120
	s_cmpk_lt_u32 s45, 7200
	s_cbranch_scc1 .Ltup1_pro1_drow_cf
	s_sub_u32 s47, s45, 7200
	s_movk_i32 s43, 5248

; __global__ void __launch_bounds__(512, 2) mk_fwd(Args args) {
;     ...
;         for (int it = gw; it < n_items0; it += NGW) {
;             int r = it;
;             if (r < I_IN) { const int nblk = 9248 / 32, kb = r / nblk, nb = r % nblk; p0_transpose_item(w_in, DM, 9248, WinT, 64 * kb, 32 * nb, win_dest_row(32 * nb), scr, lane); continue; } r -= I_IN;
.Ltup1_body0:
	s_mov_b32 s54, 0
	s_cmp_eq_u32 s53, 0
	s_cbranch_scc1 .Ltup1_noload0
	s_cmpk_lt_u32 s11, 20256
	s_cbranch_scc0 .Ltup1_noload0
	s_cmpk_lt_u32 s11, 9248
	s_cbranch_scc0 .Ltup1_m0_notin
	s_mul_hi_u32 s40, s11, 14861479
	s_mul_i32 s42, s40, 289
	s_sub_u32 s41, s11, s42
	s_mul_i32 s42, s40, 2367488
	s_lshl_b32 s43, s41, 7
	s_add_u32 s42, s42, s43
	s_add_u32 s26, s12, s42
	s_addc_u32 s27, s13, 0
	s_mov_b32 s28, 36992
	s_lshl_b32 s45, s41, 5
	s_mov_b32 s46, s45
	s_cmpk_lt_u32 s45, 5120
	s_cbranch_scc1 .Ltup1_m0_drow_done
	s_movk_i32 s46, 9216
	s_cmpk_lt_u32 s45, 5152
	s_cbranch_scc1 .Ltup1_m0_drow_done
	s_sub_u32 s47, s45, 5152
	s_movk_i32 s43, 5120
	s_cmpk_lt_u32 s45, 7200
	s_cbranch_scc1 .Ltup1_m0_drow_cf
	s_sub_u32 s47, s45, 7200
	s_movk_i32 s43, 5248

; #define SEAM(k) do { if (IN(k) && IN((k) + 1)) xcd_barrier(gbar); } while (0)
; __device__ __forceinline__ void xcd_barrier(const XcdBarrier& b) {
;     asm volatile("s_waitcnt vmcnt(0)" ::: "memory");
;     __syncthreads();
;     if (threadIdx.x == 0) {
;         unsigned* bar = b.bar;
;         __builtin_amdgcn_s_waitcnt(0);
;         unsigned nloc = b.st[0], nx = b.st[1];
;         if (nloc == 0u) { xcd_barrier_complete(bar, b.x, nloc, nx); b.st[0] = nloc; b.st[1] = nx; }
; __global__ void __launch_bounds__(512, 2) mk_fwd(Args args) {
;     ...
;     SEAM(0);
.Ltup1_done:
.Ltup1_skip:
	v_readlane_b32 s3, v254, 0
	v_readlane_b32 s4, v254, 1
	v_readlane_b32 s8, v254, 2
	v_readlane_b32 s9, v254, 3
	v_readlane_b32 s10, v254, 4
	v_readlane_b32 s11, v254, 5
	v_readlane_b32 s12, v254, 6
	v_readlane_b32 s13, v254, 7
	v_readlane_b32 s14, v254, 8
	v_readlane_b32 s15, v254, 9
	v_readlane_b32 s16, v254, 10
	v_readlane_b32 s17, v254, 11
	v_readlane_b32 s18, v254, 12
	v_readlane_b32 s19, v254, 13
	v_readlane_b32 s20, v254, 14
	v_readlane_b32 s21, v254, 15
	v_readlane_b32 s22, v254, 16
	v_readlane_b32 s23, v254, 17
	v_readlane_b32 s24, v254, 18
	v_readlane_b32 s25, v254, 19
	v_readlane_b32 s26, v254, 20
	v_readlane_b32 s27, v254, 21
	v_readlane_b32 s28, v254, 22
	v_readlane_b32 s29, v254, 23
	v_readlane_b32 s30, v254, 24
	v_readlane_b32 s31, v254, 25
	v_readlane_b32 s32, v254, 26
	v_readlane_b32 s33, v254, 27
	v_readlane_b32 s34, v254, 28
	v_readlane_b32 s35, v254, 29
	v_readlane_b32 s36, v254, 30
	v_readlane_b32 s37, v254, 31
	v_readlane_b32 s38, v254, 32
	v_readlane_b32 s39, v254, 33
	v_readlane_b32 s40, v254, 34
	v_readlane_b32 s41, v254, 35
	v_readlane_b32 s42, v254, 36
	v_readlane_b32 s43, v254, 37
	v_readlane_b32 s44, v254, 38
	v_readlane_b32 s45, v254, 39
	v_readlane_b32 s46, v254, 40
	v_readlane_b32 s47, v254, 41
	v_readlane_b32 s48, v254, 42
	v_readlane_b32 s49, v254, 43
	v_readlane_b32 s50, v254, 44
	v_readlane_b32 s51, v254, 45
	v_readlane_b32 s52, v254, 46
	v_readlane_b32 s53, v254, 47
	v_readlane_b32 s54, v254, 48
	v_readlane_b32 s55, v254, 49
	s_nop 4
	s_cmp_gt_i32 s89, 2
	s_cselect_b64 s[4:5], -1, 0
	s_and_b64 s[0:1], s[0:1], s[4:5]
	s_andn2_b64 vcc, exec, s[0:1]
	s_cbranch_vccnz .LBB0_207
	s_waitcnt vmcnt(0)
	s_waitcnt vmcnt(0) lgkmcnt(0)
	s_barrier
	s_mov_b64 s[0:1], exec
	v_readlane_b32 s6, v253, 4
	v_readlane_b32 s7, v253, 5
	s_and_b64 s[6:7], s[0:1], s[6:7]
	s_mov_b64 exec, s[6:7]
	s_cbranch_execz .LBB0_206
	s_add_i32 s3, 0, 0x23fc0
	v_mov_b32_e32 v0, s3
	s_waitcnt vmcnt(0) expcnt(0) lgkmcnt(0)
	ds_read_b32 v2, v0
	s_add_i32 s3, 0, 0x23fc4
	v_mov_b32_e32 v0, s3
	ds_read_b32 v0, v0
	s_waitcnt lgkmcnt(1)
	v_cmp_ne_u32_e32 vcc, 0, v2
	s_cbranch_vccnz .LBB0_170
	v_readlane_b32 s6, v253, 0
	v_readlane_b32 s7, v253, 1
	s_load_dwordx2 s[10:11], s[6:7], 0x4
	s_add_u32 s6, s74, 0x1000
	s_addc_u32 s7, s75, 0
	s_add_u32 s8, s74, 0x1100
	s_addc_u32 s9, s75, 0
	s_waitcnt lgkmcnt(0)
	s_mul_i32 s3, s10, s94
	s_add_u32 s10, s74, 0x1200
	s_mul_i32 s3, s3, s11
	s_addc_u32 s11, s75, 0
	s_add_u32 s12, s74, 0x1300
	s_addc_u32 s13, s75, 0
	s_mov_b32 s20, 1
	v_mov_b32_e32 v16, 0
	s_branch .LBB0_158

; #define LAS __attribute__((address_space(3)))
; __device__ __forceinline__ int ltid() { int t = threadIdx.x; asm volatile("" : "+v"(t)); return t; }
; __device__ __forceinline__ KArgs ka_get() { KArgs p = (KArgs)__builtin_amdgcn_kernarg_segment_ptr(); asm volatile("" : "+s"(p)); return p; }
; __global__ void __launch_bounds__(512, 2) mk_fwd(Args args) {
;     ...
;     if (IN(0)) { const KArgs KA = ka_get(); const int tid = ltid(), lane = tid & 63, wave = __builtin_amdgcn_readfirstlane(tid >> 6); (void)lane; (void)wave;
;         LAS float* scr = (LAS float*)(lds + wave * 16384);
;         const int gw = bx * 8 + wave, NGW = G * 8;
;         constexpr int I_IN = (DM / 64) * (9248 / 32), I_OUT = (DMIX / 64) * (DM / 32), I_UP = (DM / 64) * (FF2 / 32), I_DN = (FF / 64) * (DM / 32);
;         constexpr int n_items0 = I_IN + I_OUT + I_UP + I_DN;
;         for (int it = gw; it < n_items0; it += NGW) {
;             int r = it;
;             if (r < I_IN) { const int nblk = 9248 / 32, kb = r / nblk, nb = r % nblk; p0_transpose_item(w_in, DM, 9248, WinT, 64 * kb, 32 * nb, win_dest_row(32 * nb), scr, lane); continue; } r -= I_IN;
.LBB0_491:
	v_writelane_b32 v254, s3, 0
	v_writelane_b32 v254, s4, 1
	v_writelane_b32 v254, s8, 2
	v_writelane_b32 v254, s9, 3
	v_writelane_b32 v254, s10, 4
	v_writelane_b32 v254, s11, 5
	v_writelane_b32 v254, s12, 6
	v_writelane_b32 v254, s13, 7
	v_writelane_b32 v254, s14, 8
	v_writelane_b32 v254, s15, 9
	v_writelane_b32 v254, s16, 10
	v_writelane_b32 v254, s17, 11
	v_writelane_b32 v254, s18, 12
	v_writelane_b32 v254, s19, 13
	v_writelane_b32 v254, s20, 14
	v_writelane_b32 v254, s21, 15
	v_writelane_b32 v254, s22, 16
	v_writelane_b32 v254, s23, 17
	v_writelane_b32 v254, s24, 18
	v_writelane_b32 v254, s25, 19
	v_writelane_b32 v254, s26, 20
	v_writelane_b32 v254, s27, 21
	v_writelane_b32 v254, s28, 22
	v_writelane_b32 v254, s29, 23
	v_writelane_b32 v254, s30, 24
	v_writelane_b32 v254, s31, 25
	v_writelane_b32 v254, s32, 26
	v_writelane_b32 v254, s33, 27
	v_writelane_b32 v254, s34, 28
	v_writelane_b32 v254, s35, 29
	v_writelane_b32 v254, s36, 30
	v_writelane_b32 v254, s37, 31
	v_writelane_b32 v254, s38, 32
	v_writelane_b32 v254, s39, 33
	v_writelane_b32 v254, s40, 34
	v_writelane_b32 v254, s41, 35
	v_writelane_b32 v254, s42, 36
	v_writelane_b32 v254, s43, 37
	v_writelane_b32 v254, s44, 38
	v_writelane_b32 v254, s45, 39
	v_writelane_b32 v254, s46, 40
	v_writelane_b32 v254, s47, 41
	v_writelane_b32 v254, s48, 42
	v_writelane_b32 v254, s49, 43
	v_writelane_b32 v254, s50, 44
	v_writelane_b32 v254, s51, 45
	v_writelane_b32 v254, s52, 46
	v_writelane_b32 v254, s53, 47
	v_writelane_b32 v254, s54, 48
	v_writelane_b32 v254, s55, 49
	s_cmpk_lt_u32 s2, 128
	s_cbranch_scc1 .Ltup3_skip
	s_mov_b64 s[8:9], s[96:97]
	v_and_b32_e32 v3, 63, v212
	v_readfirstlane_b32 s4, v212
	s_sub_u32 s3, s2, 128
	s_lshl_b32 s3, s3, 3
	s_lshr_b32 s4, s4, 6
	s_add_u32 s3, s3, s4
	s_add_u32 s11, s3, 14384
	s_sub_u32 s10, s94, 128
	s_lshl_b32 s10, s10, 3
	s_cmpk_lt_u32 s11, 17456
	s_cbranch_scc0 .Ltup3_skip
	s_load_dwordx2 s[12:13], s[8:9], 0x38
	s_load_dwordx2 s[14:15], s[8:9], 0x90
	s_load_dwordx2 s[16:17], s[8:9], 0xa0
	s_load_dwordx2 s[18:19], s[8:9], 0xb8
	s_load_dwordx2 s[20:21], s[8:9], 0x98
	s_load_dwordx2 s[22:23], s[8:9], 0xd0
	v_lshrrev_b32_e32 v4, 3, v3
	v_and_b32_e32 v7, 7, v3
	v_lshlrev_b32_e32 v5, 4, v7
	v_lshlrev_b32_e32 v6, 5, v7
	s_lshl_b32 s24, s4, 14
	v_lshl_add_u32 v16, v4, 7, s24
	v_xor_b32_e32 v8, 0, v7
	v_lshl_add_u32 v8, v8, 4, v16
	v_xor_b32_e32 v9, 1, v7
	v_lshl_add_u32 v9, v9, 4, v16
	v_xor_b32_e32 v10, 2, v7
	v_lshl_add_u32 v10, v10, 4, v16
	v_xor_b32_e32 v11, 3, v7
	v_lshl_add_u32 v11, v11, 4, v16
	v_xor_b32_e32 v12, 4, v7
	v_lshl_add_u32 v12, v12, 4, v16
	v_xor_b32_e32 v13, 5, v7
	v_lshl_add_u32 v13, v13, 4, v16
	v_xor_b32_e32 v14, 6, v7
	v_lshl_add_u32 v14, v14, 4, v16
	v_xor_b32_e32 v15, 7, v7
	v_lshl_add_u32 v15, v15, 4, v16
	v_lshlrev_b32_e32 v20, 2, v7
	v_lshl_add_u32 v21, v7, 10, s24
	v_add_u32_e32 v16, 0, v4
	v_xor_b32_e32 v16, v16, v20
	v_lshl_add_u32 v16, v16, 2, v21
	v_add_u32_e32 v17, 8, v4
	v_xor_b32_e32 v17, v17, v20
	v_lshl_add_u32 v17, v17, 2, v21
	v_add_u32_e32 v18, 16, v4
	v_xor_b32_e32 v18, v18, v20
	v_lshl_add_u32 v18, v18, 2, v21
	v_add_u32_e32 v19, 24, v4
	v_xor_b32_e32 v19, v19, v20
	v_lshl_add_u32 v19, v19, 2, v21
	s_waitcnt lgkmcnt(0)
	s_mov_b32 s53, 0
	s_cmpk_lt_u32 s11, 9248
	s_cbranch_scc0 .Ltup3_pro0_notin
	s_mul_hi_u32 s40, s11, 14861479
	s_mul_i32 s42, s40, 289
	s_sub_u32 s41, s11, s42
	s_mul_i32 s42, s40, 2367488
	s_lshl_b32 s43, s41, 7
	s_add_u32 s42, s42, s43
	s_add_u32 s26, s12, s42
	s_addc_u32 s27, s13, 0
	s_mov_b32 s28, 36992
	s_lshl_b32 s45, s41, 5
	s_mov_b32 s46, s45
	s_cmpk_lt_u32 s45, 5120
	s_cbranch_scc1 .Ltup3_pro0_drow_done
	s_movk_i32 s46, 9216
	s_cmpk_lt_u32 s45, 5152
	s_cbranch_scc1 .Ltup3_pro0_drow_done
	s_sub_u32 s47, s45, 5152
	s_movk_i32 s43, 5120
	s_cmpk_lt_u32 s45, 7200
	s_cbranch_scc1 .Ltup3_pro0_drow_cf
	s_sub_u32 s47, s45, 7200
	s_movk_i32 s43, 5248

; #define LAS __attribute__((address_space(3)))
; __device__ __forceinline__ void p0_transpose_item(const float* W, int K, int N, bf16_t* WT, int k0, int n0, int drow0, LAS float* scr, int lane, const float* kscale = nullptr) {
;     const float ks = kscale ? kscale[k0 + lane] : 1.f;
; #pragma unroll 8
;     for (int i = 0; i < 32; ++i) { const int kk = 2 * i + (lane >> 5); scr[kk * 33 + (lane & 31)] = W[(size_t)(k0 + kk) * N + n0 + (lane & 31)] * __shfl(ks, kk); }
.Ltup3_pro0_decoded:
	v_mad_u32_u24 v20, v4, s28, v5
	s_lshl_b32 s29, s28, 3
	s_and_b32 s42, s40, 31
	s_lshl_b32 s42, s42, 8
	s_add_u32 s34, s20, s42
	s_addc_u32 s35, s21, 0
	global_load_dwordx4 v[32:35], v6, s[34:35]
	global_load_dwordx4 v[36:39], v6, s[34:35] offset:16
	global_load_dwordx4 v[40:43], v20, s[26:27] nt
	s_add_u32 s26, s26, s29
	s_addc_u32 s27, s27, 0
	global_load_dwordx4 v[44:47], v20, s[26:27] nt
	s_add_u32 s26, s26, s29
	s_addc_u32 s27, s27, 0
	global_load_dwordx4 v[48:51], v20, s[26:27] nt
	s_add_u32 s26, s26, s29
	s_addc_u32 s27, s27, 0
	global_load_dwordx4 v[52:55], v20, s[26:27] nt
	s_add_u32 s26, s26, s29
	s_addc_u32 s27, s27, 0
	global_load_dwordx4 v[56:59], v20, s[26:27] nt
	s_add_u32 s26, s26, s29
	s_addc_u32 s27, s27, 0
	global_load_dwordx4 v[60:63], v20, s[26:27] nt
	s_add_u32 s26, s26, s29
	s_addc_u32 s27, s27, 0
	global_load_dwordx4 v[64:67], v20, s[26:27] nt
	s_add_u32 s26, s26, s29
	s_addc_u32 s27, s27, 0
	global_load_dwordx4 v[68:71], v20, s[26:27] nt
	s_add_u32 s11, s11, s10
	s_cmpk_lt_u32 s11, 17456
	s_cbranch_scc0 .Ltup3_pro_single
	s_cmpk_lt_u32 s11, 9248
	s_cbranch_scc0 .Ltup3_pro1_notin
	s_mul_hi_u32 s40, s11, 14861479
	s_mul_i32 s42, s40, 289
	s_sub_u32 s41, s11, s42
	s_mul_i32 s42, s40, 2367488
	s_lshl_b32 s43, s41, 7
	s_add_u32 s42, s42, s43
	s_add_u32 s26, s12, s42
	s_addc_u32 s27, s13, 0
	s_mov_b32 s28, 36992
	s_lshl_b32 s45, s41, 5
	s_mov_b32 s46, s45
	s_cmpk_lt_u32 s45, 5120
	s_cbranch_scc1 .Ltup3_pro1_drow_done
	s_movk_i32 s46, 9216
	s_cmpk_lt_u32 s45, 5152
	s_cbranch_scc1 .Ltup3_pro1_drow_done
	s_sub_u32 s47, s45, 5152
	s_movk_i32 s43, 5120
	s_cmpk_lt_u32 s45, 7200
	s_cbranch_scc1 .Ltup3_pro1_drow_cf
	s_sub_u32 s47, s45, 7200
	s_movk_i32 s43, 5248

; __global__ void __launch_bounds__(512, 2) mk_fwd(Args args) {
;     ...
;         for (int it = gw; it < n_items0; it += NGW) {
;             int r = it;
;             if (r < I_IN) { const int nblk = 9248 / 32, kb = r / nblk, nb = r % nblk; p0_transpose_item(w_in, DM, 9248, WinT, 64 * kb, 32 * nb, win_dest_row(32 * nb), scr, lane); continue; } r -= I_IN;
.Ltup3_body0:
	s_mov_b32 s54, 0
	s_cmp_eq_u32 s53, 0
	s_cbranch_scc1 .Ltup3_noload0
	s_cmpk_lt_u32 s11, 17456
	s_cbranch_scc0 .Ltup3_noload0
	s_cmpk_lt_u32 s11, 9248
	s_cbranch_scc0 .Ltup3_m0_notin
	s_mul_hi_u32 s40, s11, 14861479
	s_mul_i32 s42, s40, 289
	s_sub_u32 s41, s11, s42
	s_mul_i32 s42, s40, 2367488
	s_lshl_b32 s43, s41, 7
	s_add_u32 s42, s42, s43
	s_add_u32 s26, s12, s42
	s_addc_u32 s27, s13, 0
	s_mov_b32 s28, 36992
	s_lshl_b32 s45, s41, 5
	s_mov_b32 s46, s45
	s_cmpk_lt_u32 s45, 5120
	s_cbranch_scc1 .Ltup3_m0_drow_done
	s_movk_i32 s46, 9216
	s_cmpk_lt_u32 s45, 5152
	s_cbranch_scc1 .Ltup3_m0_drow_done
	s_sub_u32 s47, s45, 5152
	s_movk_i32 s43, 5120
	s_cmpk_lt_u32 s45, 7200
	s_cbranch_scc1 .Ltup3_m0_drow_cf
	s_sub_u32 s47, s45, 7200
	s_movk_i32 s43, 5248

; #define SEAM(k) do { if (IN(k) && IN((k) + 1)) xcd_barrier(gbar); } while (0)
; __device__ __forceinline__ void xcd_barrier(const XcdBarrier& b) {
;     asm volatile("s_waitcnt vmcnt(0)" ::: "memory");
;     __syncthreads();
;     if (threadIdx.x == 0) {
;         unsigned* bar = b.bar;
;         __builtin_amdgcn_s_waitcnt(0);
;         unsigned nloc = b.st[0], nx = b.st[1];
;         if (nloc == 0u) { xcd_barrier_complete(bar, b.x, nloc, nx); b.st[0] = nloc; b.st[1] = nx; }
; __global__ void __launch_bounds__(512, 2) mk_fwd(Args args) {
;     ...
;     SEAM(0);
.Ltup3_done:
.Ltup3_skip:
	v_readlane_b32 s3, v254, 0
	v_readlane_b32 s4, v254, 1
	v_readlane_b32 s8, v254, 2
	v_readlane_b32 s9, v254, 3
	v_readlane_b32 s10, v254, 4
	v_readlane_b32 s11, v254, 5
	v_readlane_b32 s12, v254, 6
	v_readlane_b32 s13, v254, 7
	v_readlane_b32 s14, v254, 8
	v_readlane_b32 s15, v254, 9
	v_readlane_b32 s16, v254, 10
	v_readlane_b32 s17, v254, 11
	v_readlane_b32 s18, v254, 12
	v_readlane_b32 s19, v254, 13
	v_readlane_b32 s20, v254, 14
	v_readlane_b32 s21, v254, 15
	v_readlane_b32 s22, v254, 16
	v_readlane_b32 s23, v254, 17
	v_readlane_b32 s24, v254, 18
	v_readlane_b32 s25, v254, 19
	v_readlane_b32 s26, v254, 20
	v_readlane_b32 s27, v254, 21
	v_readlane_b32 s28, v254, 22
	v_readlane_b32 s29, v254, 23
	v_readlane_b32 s30, v254, 24
	v_readlane_b32 s31, v254, 25
	v_readlane_b32 s32, v254, 26
	v_readlane_b32 s33, v254, 27
	v_readlane_b32 s34, v254, 28
	v_readlane_b32 s35, v254, 29
	v_readlane_b32 s36, v254, 30
	v_readlane_b32 s37, v254, 31
	v_readlane_b32 s38, v254, 32
	v_readlane_b32 s39, v254, 33
	v_readlane_b32 s40, v254, 34
	v_readlane_b32 s41, v254, 35
	v_readlane_b32 s42, v254, 36
	v_readlane_b32 s43, v254, 37
	v_readlane_b32 s44, v254, 38
	v_readlane_b32 s45, v254, 39
	v_readlane_b32 s46, v254, 40
	v_readlane_b32 s47, v254, 41
	v_readlane_b32 s48, v254, 42
	v_readlane_b32 s49, v254, 43
	v_readlane_b32 s50, v254, 44
	v_readlane_b32 s51, v254, 45
	v_readlane_b32 s52, v254, 46
	v_readlane_b32 s53, v254, 47
	v_readlane_b32 s54, v254, 48
	v_readlane_b32 s55, v254, 49
	s_nop 4
	s_cmp_gt_i32 s89, 4
	s_cselect_b64 s[0:1], -1, 0
	s_and_b64 s[4:5], s[4:5], s[0:1]
	v_readlane_b32 s90, v253, 4
	s_andn2_b64 vcc, exec, s[4:5]
	v_readlane_b32 s91, v253, 5
	s_cbranch_vccnz .LBB0_545
	s_waitcnt vmcnt(0)
	s_waitcnt vmcnt(0) lgkmcnt(0)
	s_barrier
	s_and_saveexec_b64 s[4:5], s[90:91]
	s_cbranch_execz .LBB0_544
	s_add_i32 s3, 0, 0x23fc0
	v_mov_b32_e32 v0, s3
	s_waitcnt vmcnt(0) expcnt(0) lgkmcnt(0)
	ds_read_b32 v2, v0
	s_add_i32 s3, 0, 0x23fc4
	v_mov_b32_e32 v0, s3
	ds_read_b32 v0, v0
	s_waitcnt lgkmcnt(1)
	v_cmp_ne_u32_e32 vcc, 0, v2
	s_cbranch_vccnz .LBB0_508
	v_readlane_b32 s6, v253, 0
	v_readlane_b32 s7, v253, 1
	s_load_dwordx2 s[10:11], s[6:7], 0x4
	s_add_u32 s6, s74, 0x1000
	s_addc_u32 s7, s75, 0
	s_add_u32 s8, s74, 0x1100
	s_addc_u32 s9, s75, 0
	s_waitcnt lgkmcnt(0)
	s_mul_i32 s3, s10, s94
	s_add_u32 s10, s74, 0x1200
	s_mul_i32 s3, s3, s11
	s_addc_u32 s11, s75, 0
	s_add_u32 s12, s74, 0x1300
	s_addc_u32 s13, s75, 0
	s_mov_b32 s20, 1
	v_mov_b32_e32 v16, 0
	s_branch .LBB0_496

; #define LAS __attribute__((address_space(3)))
; __device__ __forceinline__ int ltid() { int t = threadIdx.x; asm volatile("" : "+v"(t)); return t; }
; __device__ __forceinline__ KArgs ka_get() { KArgs p = (KArgs)__builtin_amdgcn_kernarg_segment_ptr(); asm volatile("" : "+s"(p)); return p; }
; __global__ void __launch_bounds__(512, 2) mk_fwd(Args args) {
;     ...
;     if (IN(0)) { const KArgs KA = ka_get(); const int tid = ltid(), lane = tid & 63, wave = __builtin_amdgcn_readfirstlane(tid >> 6); (void)lane; (void)wave;
;         LAS float* scr = (LAS float*)(lds + wave * 16384);
;         const int gw = bx * 8 + wave, NGW = G * 8;
;         constexpr int I_IN = (DM / 64) * (9248 / 32), I_OUT = (DMIX / 64) * (DM / 32), I_UP = (DM / 64) * (FF2 / 32), I_DN = (FF / 64) * (DM / 32);
;         constexpr int n_items0 = I_IN + I_OUT + I_UP + I_DN;
;         for (int it = gw; it < n_items0; it += NGW) {
;             int r = it;
;             if (r < I_IN) { const int nblk = 9248 / 32, kb = r / nblk, nb = r % nblk; p0_transpose_item(w_in, DM, 9248, WinT, 64 * kb, 32 * nb, win_dest_row(32 * nb), scr, lane); continue; } r -= I_IN;
.LBB0_675:
	v_writelane_b32 v254, s3, 0
	v_writelane_b32 v254, s4, 1
	v_writelane_b32 v254, s8, 2
	v_writelane_b32 v254, s9, 3
	v_writelane_b32 v254, s10, 4
	v_writelane_b32 v254, s11, 5
	v_writelane_b32 v254, s12, 6
	v_writelane_b32 v254, s13, 7
	v_writelane_b32 v254, s14, 8
	v_writelane_b32 v254, s15, 9
	v_writelane_b32 v254, s16, 10
	v_writelane_b32 v254, s17, 11
	v_writelane_b32 v254, s18, 12
	v_writelane_b32 v254, s19, 13
	v_writelane_b32 v254, s20, 14
	v_writelane_b32 v254, s21, 15
	v_writelane_b32 v254, s22, 16
	v_writelane_b32 v254, s23, 17
	v_writelane_b32 v254, s24, 18
	v_writelane_b32 v254, s25, 19
	v_writelane_b32 v254, s26, 20
	v_writelane_b32 v254, s27, 21
	v_writelane_b32 v254, s28, 22
	v_writelane_b32 v254, s29, 23
	v_writelane_b32 v254, s30, 24
	v_writelane_b32 v254, s31, 25
	v_writelane_b32 v254, s32, 26
	v_writelane_b32 v254, s33, 27
	v_writelane_b32 v254, s34, 28
	v_writelane_b32 v254, s35, 29
	v_writelane_b32 v254, s36, 30
	v_writelane_b32 v254, s37, 31
	v_writelane_b32 v254, s38, 32
	v_writelane_b32 v254, s39, 33
	v_writelane_b32 v254, s40, 34
	v_writelane_b32 v254, s41, 35
	v_writelane_b32 v254, s42, 36
	v_writelane_b32 v254, s43, 37
	v_writelane_b32 v254, s44, 38
	v_writelane_b32 v254, s45, 39
	v_writelane_b32 v254, s46, 40
	v_writelane_b32 v254, s47, 41
	v_writelane_b32 v254, s48, 42
	v_writelane_b32 v254, s49, 43
	v_writelane_b32 v254, s50, 44
	v_writelane_b32 v254, s51, 45
	v_writelane_b32 v254, s52, 46
	v_writelane_b32 v254, s53, 47
	v_writelane_b32 v254, s54, 48
	v_writelane_b32 v254, s55, 49
	s_cmpk_lt_u32 s2, 128
	s_cbranch_scc1 .Ltup2_skip
	s_mov_b64 s[8:9], s[96:97]
	v_and_b32_e32 v3, 63, v212
	v_readfirstlane_b32 s4, v212
	s_sub_u32 s3, s2, 128
	s_lshl_b32 s3, s3, 3
	s_lshr_b32 s4, s4, 6
	s_add_u32 s3, s3, s4
	s_add_u32 s11, s3, 20256
	s_sub_u32 s10, s94, 128
	s_lshl_b32 s10, s10, 3
	s_cmpk_lt_u32 s11, 24352
	s_cbranch_scc0 .Ltup2_skip
	s_load_dwordx2 s[12:13], s[8:9], 0x38
	s_load_dwordx2 s[14:15], s[8:9], 0x90
	s_load_dwordx2 s[16:17], s[8:9], 0xa0
	s_load_dwordx2 s[18:19], s[8:9], 0xb8
	s_load_dwordx2 s[20:21], s[8:9], 0x98
	s_load_dwordx2 s[22:23], s[8:9], 0xd0
	v_lshrrev_b32_e32 v4, 3, v3
	v_and_b32_e32 v7, 7, v3
	v_lshlrev_b32_e32 v5, 4, v7
	v_lshlrev_b32_e32 v6, 5, v7
	s_lshl_b32 s24, s4, 14
	v_lshl_add_u32 v16, v4, 7, s24
	v_xor_b32_e32 v8, 0, v7
	v_lshl_add_u32 v8, v8, 4, v16
	v_xor_b32_e32 v9, 1, v7
	v_lshl_add_u32 v9, v9, 4, v16
	v_xor_b32_e32 v10, 2, v7
	v_lshl_add_u32 v10, v10, 4, v16
	v_xor_b32_e32 v11, 3, v7
	v_lshl_add_u32 v11, v11, 4, v16
	v_xor_b32_e32 v12, 4, v7
	v_lshl_add_u32 v12, v12, 4, v16
	v_xor_b32_e32 v13, 5, v7
	v_lshl_add_u32 v13, v13, 4, v16
	v_xor_b32_e32 v14, 6, v7
	v_lshl_add_u32 v14, v14, 4, v16
	v_xor_b32_e32 v15, 7, v7
	v_lshl_add_u32 v15, v15, 4, v16
	v_lshlrev_b32_e32 v20, 2, v7
	v_lshl_add_u32 v21, v7, 10, s24
	v_add_u32_e32 v16, 0, v4
	v_xor_b32_e32 v16, v16, v20
	v_lshl_add_u32 v16, v16, 2, v21
	v_add_u32_e32 v17, 8, v4
	v_xor_b32_e32 v17, v17, v20
	v_lshl_add_u32 v17, v17, 2, v21
	v_add_u32_e32 v18, 16, v4
	v_xor_b32_e32 v18, v18, v20
	v_lshl_add_u32 v18, v18, 2, v21
	v_add_u32_e32 v19, 24, v4
	v_xor_b32_e32 v19, v19, v20
	v_lshl_add_u32 v19, v19, 2, v21
	s_waitcnt lgkmcnt(0)
	s_mov_b32 s53, 0
	s_cmpk_lt_u32 s11, 9248
	s_cbranch_scc0 .Ltup2_pro0_notin
	s_mul_hi_u32 s40, s11, 14861479
	s_mul_i32 s42, s40, 289
	s_sub_u32 s41, s11, s42
	s_mul_i32 s42, s40, 2367488
	s_lshl_b32 s43, s41, 7
	s_add_u32 s42, s42, s43
	s_add_u32 s26, s12, s42
	s_addc_u32 s27, s13, 0
	s_mov_b32 s28, 36992
	s_lshl_b32 s45, s41, 5
	s_mov_b32 s46, s45
	s_cmpk_lt_u32 s45, 5120
	s_cbranch_scc1 .Ltup2_pro0_drow_done
	s_movk_i32 s46, 9216
	s_cmpk_lt_u32 s45, 5152
	s_cbranch_scc1 .Ltup2_pro0_drow_done
	s_sub_u32 s47, s45, 5152
	s_movk_i32 s43, 5120
	s_cmpk_lt_u32 s45, 7200
	s_cbranch_scc1 .Ltup2_pro0_drow_cf
	s_sub_u32 s47, s45, 7200
	s_movk_i32 s43, 5248

; #define LAS __attribute__((address_space(3)))
; __device__ __forceinline__ void p0_transpose_item(const float* W, int K, int N, bf16_t* WT, int k0, int n0, int drow0, LAS float* scr, int lane, const float* kscale = nullptr) {
;     const float ks = kscale ? kscale[k0 + lane] : 1.f;
; #pragma unroll 8
;     for (int i = 0; i < 32; ++i) { const int kk = 2 * i + (lane >> 5); scr[kk * 33 + (lane & 31)] = W[(size_t)(k0 + kk) * N + n0 + (lane & 31)] * __shfl(ks, kk); }
.Ltup2_pro0_decoded:
	v_mad_u32_u24 v20, v4, s28, v5
	s_lshl_b32 s29, s28, 3
	s_and_b32 s42, s40, 31
	s_lshl_b32 s42, s42, 8
	s_add_u32 s34, s20, s42
	s_addc_u32 s35, s21, 0
	global_load_dwordx4 v[32:35], v6, s[34:35]
	global_load_dwordx4 v[36:39], v6, s[34:35] offset:16
	global_load_dwordx4 v[40:43], v20, s[26:27] nt
	s_add_u32 s26, s26, s29
	s_addc_u32 s27, s27, 0
	global_load_dwordx4 v[44:47], v20, s[26:27] nt
	s_add_u32 s26, s26, s29
	s_addc_u32 s27, s27, 0
	global_load_dwordx4 v[48:51], v20, s[26:27] nt
	s_add_u32 s26, s26, s29
	s_addc_u32 s27, s27, 0
	global_load_dwordx4 v[52:55], v20, s[26:27] nt
	s_add_u32 s26, s26, s29
	s_addc_u32 s27, s27, 0
	global_load_dwordx4 v[56:59], v20, s[26:27] nt
	s_add_u32 s26, s26, s29
	s_addc_u32 s27, s27, 0
	global_load_dwordx4 v[60:63], v20, s[26:27] nt
	s_add_u32 s26, s26, s29
	s_addc_u32 s27, s27, 0
	global_load_dwordx4 v[64:67], v20, s[26:27] nt
	s_add_u32 s26, s26, s29
	s_addc_u32 s27, s27, 0
	global_load_dwordx4 v[68:71], v20, s[26:27] nt
	s_add_u32 s11, s11, s10
	s_cmpk_lt_u32 s11, 24352
	s_cbranch_scc0 .Ltup2_pro_single
	s_cmpk_lt_u32 s11, 9248
	s_cbranch_scc0 .Ltup2_pro1_notin
	s_mul_hi_u32 s40, s11, 14861479
	s_mul_i32 s42, s40, 289
	s_sub_u32 s41, s11, s42
	s_mul_i32 s42, s40, 2367488
	s_lshl_b32 s43, s41, 7
	s_add_u32 s42, s42, s43
	s_add_u32 s26, s12, s42
	s_addc_u32 s27, s13, 0
	s_mov_b32 s28, 36992
	s_lshl_b32 s45, s41, 5
	s_mov_b32 s46, s45
	s_cmpk_lt_u32 s45, 5120
	s_cbranch_scc1 .Ltup2_pro1_drow_done
	s_movk_i32 s46, 9216
	s_cmpk_lt_u32 s45, 5152
	s_cbranch_scc1 .Ltup2_pro1_drow_done
	s_sub_u32 s47, s45, 5152
	s_movk_i32 s43, 5120
	s_cmpk_lt_u32 s45, 7200
	s_cbranch_scc1 .Ltup2_pro1_drow_cf
	s_sub_u32 s47, s45, 7200
	s_movk_i32 s43, 5248

; __global__ void __launch_bounds__(512, 2) mk_fwd(Args args) {
;     ...
;         for (int it = gw; it < n_items0; it += NGW) {
;             int r = it;
;             if (r < I_IN) { const int nblk = 9248 / 32, kb = r / nblk, nb = r % nblk; p0_transpose_item(w_in, DM, 9248, WinT, 64 * kb, 32 * nb, win_dest_row(32 * nb), scr, lane); continue; } r -= I_IN;
.Ltup2_body0:
	s_mov_b32 s54, 0
	s_cmp_eq_u32 s53, 0
	s_cbranch_scc1 .Ltup2_noload0
	s_cmpk_lt_u32 s11, 24352
	s_cbranch_scc0 .Ltup2_noload0
	s_cmpk_lt_u32 s11, 9248
	s_cbranch_scc0 .Ltup2_m0_notin
	s_mul_hi_u32 s40, s11, 14861479
	s_mul_i32 s42, s40, 289
	s_sub_u32 s41, s11, s42
	s_mul_i32 s42, s40, 2367488
	s_lshl_b32 s43, s41, 7
	s_add_u32 s42, s42, s43
	s_add_u32 s26, s12, s42
	s_addc_u32 s27, s13, 0
	s_mov_b32 s28, 36992
	s_lshl_b32 s45, s41, 5
	s_mov_b32 s46, s45
	s_cmpk_lt_u32 s45, 5120
	s_cbranch_scc1 .Ltup2_m0_drow_done
	s_movk_i32 s46, 9216
	s_cmpk_lt_u32 s45, 5152
	s_cbranch_scc1 .Ltup2_m0_drow_done
	s_sub_u32 s47, s45, 5152
	s_movk_i32 s43, 5120
	s_cmpk_lt_u32 s45, 7200
	s_cbranch_scc1 .Ltup2_m0_drow_cf
	s_sub_u32 s47, s45, 7200
	s_movk_i32 s43, 5248

; #define SEAM(k) do { if (IN(k) && IN((k) + 1)) xcd_barrier(gbar); } while (0)
; __device__ __forceinline__ void xcd_barrier(const XcdBarrier& b) {
;     asm volatile("s_waitcnt vmcnt(0)" ::: "memory");
;     __syncthreads();
;     if (threadIdx.x == 0) {
;         unsigned* bar = b.bar;
;         __builtin_amdgcn_s_waitcnt(0);
;         unsigned nloc = b.st[0], nx = b.st[1];
;         if (nloc == 0u) { xcd_barrier_complete(bar, b.x, nloc, nx); b.st[0] = nloc; b.st[1] = nx; }
; __global__ void __launch_bounds__(512, 2) mk_fwd(Args args) {
;     ...
;     SEAM(0);
.Ltup2_done:
.Ltup2_skip:
	v_readlane_b32 s3, v254, 0
	v_readlane_b32 s4, v254, 1
	v_readlane_b32 s8, v254, 2
	v_readlane_b32 s9, v254, 3
	v_readlane_b32 s10, v254, 4
	v_readlane_b32 s11, v254, 5
	v_readlane_b32 s12, v254, 6
	v_readlane_b32 s13, v254, 7
	v_readlane_b32 s14, v254, 8
	v_readlane_b32 s15, v254, 9
	v_readlane_b32 s16, v254, 10
	v_readlane_b32 s17, v254, 11
	v_readlane_b32 s18, v254, 12
	v_readlane_b32 s19, v254, 13
	v_readlane_b32 s20, v254, 14
	v_readlane_b32 s21, v254, 15
	v_readlane_b32 s22, v254, 16
	v_readlane_b32 s23, v254, 17
	v_readlane_b32 s24, v254, 18
	v_readlane_b32 s25, v254, 19
	v_readlane_b32 s26, v254, 20
	v_readlane_b32 s27, v254, 21
	v_readlane_b32 s28, v254, 22
	v_readlane_b32 s29, v254, 23
	v_readlane_b32 s30, v254, 24
	v_readlane_b32 s31, v254, 25
	v_readlane_b32 s32, v254, 26
	v_readlane_b32 s33, v254, 27
	v_readlane_b32 s34, v254, 28
	v_readlane_b32 s35, v254, 29
	v_readlane_b32 s36, v254, 30
	v_readlane_b32 s37, v254, 31
	v_readlane_b32 s38, v254, 32
	v_readlane_b32 s39, v254, 33
	v_readlane_b32 s40, v254, 34
	v_readlane_b32 s41, v254, 35
	v_readlane_b32 s42, v254, 36
	v_readlane_b32 s43, v254, 37
	v_readlane_b32 s44, v254, 38
	v_readlane_b32 s45, v254, 39
	v_readlane_b32 s46, v254, 40
	v_readlane_b32 s47, v254, 41
	v_readlane_b32 s48, v254, 42
	v_readlane_b32 s49, v254, 43
	v_readlane_b32 s50, v254, 44
	v_readlane_b32 s51, v254, 45
	v_readlane_b32 s52, v254, 46
	v_readlane_b32 s53, v254, 47
	v_readlane_b32 s54, v254, 48
	v_readlane_b32 s55, v254, 49
	s_nop 4
	s_cmp_gt_i32 s89, 6
	s_waitcnt lgkmcnt(0)
	s_cselect_b64 s[0:1], -1, 0
	s_and_b64 s[4:5], s[6:7], s[0:1]
	s_andn2_b64 vcc, exec, s[4:5]
	s_cbranch_vccnz .LBB0_729
	s_waitcnt vmcnt(0)
	s_waitcnt vmcnt(0)
	s_barrier
	s_and_saveexec_b64 s[4:5], s[90:91]
	s_cbranch_execz .LBB0_728
	s_add_i32 s3, 0, 0x23fc0
	v_mov_b32_e32 v0, s3
	s_waitcnt vmcnt(0) expcnt(0) lgkmcnt(0)
	ds_read_b32 v2, v0
	s_add_i32 s3, 0, 0x23fc4
	v_mov_b32_e32 v0, s3
	ds_read_b32 v0, v0
	s_waitcnt lgkmcnt(1)
	v_cmp_ne_u32_e32 vcc, 0, v2
	s_cbranch_vccnz .LBB0_692
	v_readlane_b32 s6, v253, 0
	v_readlane_b32 s7, v253, 1
	s_load_dwordx2 s[10:11], s[6:7], 0x4
	s_add_u32 s6, s74, 0x1000
	s_addc_u32 s7, s75, 0
	s_add_u32 s8, s74, 0x1100
	s_addc_u32 s9, s75, 0
	s_waitcnt lgkmcnt(0)
	s_mul_i32 s3, s10, s94
	s_add_u32 s10, s74, 0x1200
	s_mul_i32 s3, s3, s11
	s_addc_u32 s11, s75, 0
	s_add_u32 s12, s74, 0x1300
	s_addc_u32 s13, s75, 0
	s_mov_b32 s20, 1
	v_mov_b32_e32 v16, 0
	s_branch .LBB0_680

; __device__ __forceinline__ float siluf_(float x) { return x * __builtin_amdgcn_rcpf(1.f + __expf(-x)); }
; template <int NT, bool SAMPLE>
; __device__ __forceinline__ void ffn_item(const bf16_t* U, int row0, bool has_hist, const float* st, int cgi, const float* w, const float* bias, bf16_t* ACT, float* state_out) {
;     ...
;     for (int t = 0; t < NT; ++t) {
;         float cg_[8], cv_[8], o[8];
;         unpack8(rg[t], cg_); unpack8(rv[t], cv_);
; #pragma unroll
;         for (int e = 0; e < 8; ++e) {
;             const float gg = g0[e] * wg[0][e] + g1[e] * wg[1][e] + cg_[e] * wg[2][e] + bg[e];
;             const float vv = v0[e] * wv[0][e] + v1[e] * wv[1][e] + cv_[e] * wv[2][e] + bvv[e];
;             o[e] = siluf_(gg) * vv; g0[e] = g1[e]; g1[e] = cg_[e]; v0[e] = v1[e]; v1[e] = cv_[e]; }
;         *(u32x4*)(ACT + (size_t)(row0 + t) * FF + c0) = pack8(o);
.Lepi7_nostate3:
	s_waitcnt vmcnt(16)
	v_mov_b32_dpp v244, v92 row_shr:1 row_mask:0xf bank_mask:0xf
	v_mov_b32_dpp v245, v76 row_shr:1 row_mask:0xf bank_mask:0xf
	v_mov_b32_dpp v246, v84 row_shr:1 row_mask:0xf bank_mask:0xf
	v_mov_b32_dpp v247, v68 row_shr:1 row_mask:0xf bank_mask:0xf
	v_fma_f32 v248, v124, v208, v228
	v_fma_f32 v144, v116, v220, v236
	v_fma_f32 v249, v108, v208, v228
	v_fma_f32 v145, v100, v220, v236
	v_fma_f32 v250, v92, v208, v228
	v_fma_f32 v137, v84, v220, v236
	v_fma_f32 v251, v76, v208, v228
	v_fma_f32 v166, v68, v220, v236
	v_fmac_f32_e32 v248, v245, v192
	v_fmac_f32_e32 v144, v247, v200
	v_fmac_f32_e32 v249, v124, v192
	v_fmac_f32_e32 v145, v116, v200
	v_fmac_f32_e32 v250, v108, v192
	v_fmac_f32_e32 v137, v100, v200
	v_fmac_f32_e32 v251, v92, v192
	v_fmac_f32_e32 v166, v84, v200
	v_fmac_f32_e32 v248, v244, v176
	v_fmac_f32_e32 v144, v246, v184
	v_fmac_f32_e32 v249, v245, v176
	v_fmac_f32_e32 v145, v247, v184
	v_fmac_f32_e32 v250, v124, v176
	v_fmac_f32_e32 v137, v116, v184
	v_fmac_f32_e32 v251, v108, v176
	v_fmac_f32_e32 v166, v100, v184
	v_mul_f32_e32 v167, 0xbfb8aa3b, v248
	v_mul_f32_e32 v213, 0xbfb8aa3b, v249
	v_mul_f32_e32 v214, 0xbfb8aa3b, v250
	v_mul_f32_e32 v215, 0xbfb8aa3b, v251
	v_exp_f32_e32 v167, v167
	v_exp_f32_e32 v213, v213
	v_exp_f32_e32 v214, v214
	v_exp_f32_e32 v215, v215
	v_add_f32_e32 v167, 1.0, v167
	v_add_f32_e32 v213, 1.0, v213
	v_add_f32_e32 v214, 1.0, v214
	v_add_f32_e32 v215, 1.0, v215
	v_rcp_f32_e32 v167, v167
	v_rcp_f32_e32 v213, v213
	v_rcp_f32_e32 v214, v214
	v_rcp_f32_e32 v215, v215
	v_mul_f32_e32 v248, v248, v144
	v_mul_f32_e32 v249, v249, v145
	v_mul_f32_e32 v250, v250, v137
	v_mul_f32_e32 v251, v251, v166
	v_mul_f32_e32 v124, v248, v167
	v_mul_f32_e32 v108, v249, v213
	v_mul_f32_e32 v92, v250, v214
	v_mul_f32_e32 v76, v251, v215
	v_mov_b32_dpp v244, v93 row_shr:1 row_mask:0xf bank_mask:0xf
	v_mov_b32_dpp v245, v77 row_shr:1 row_mask:0xf bank_mask:0xf
	v_mov_b32_dpp v246, v85 row_shr:1 row_mask:0xf bank_mask:0xf
	v_mov_b32_dpp v247, v69 row_shr:1 row_mask:0xf bank_mask:0xf
	v_fma_f32 v248, v125, v209, v229
	v_fma_f32 v144, v117, v221, v237
	v_fma_f32 v249, v109, v209, v229
	v_fma_f32 v145, v101, v221, v237
	v_fma_f32 v250, v93, v209, v229
	v_fma_f32 v137, v85, v221, v237
	v_fma_f32 v251, v77, v209, v229
	v_fma_f32 v166, v69, v221, v237
	v_fmac_f32_e32 v248, v245, v193
	v_fmac_f32_e32 v144, v247, v201
	v_fmac_f32_e32 v249, v125, v193
	v_fmac_f32_e32 v145, v117, v201
	v_fmac_f32_e32 v250, v109, v193
	v_fmac_f32_e32 v137, v101, v201
	v_fmac_f32_e32 v251, v93, v193
	v_fmac_f32_e32 v166, v85, v201
	v_fmac_f32_e32 v248, v244, v177
	v_fmac_f32_e32 v144, v246, v185
	v_fmac_f32_e32 v249, v245, v177
	v_fmac_f32_e32 v145, v247, v185
	v_fmac_f32_e32 v250, v125, v177
	v_fmac_f32_e32 v137, v117, v185
	v_fmac_f32_e32 v251, v109, v177
	v_fmac_f32_e32 v166, v101, v185
	v_mul_f32_e32 v167, 0xbfb8aa3b, v248
	v_mul_f32_e32 v213, 0xbfb8aa3b, v249
	v_mul_f32_e32 v214, 0xbfb8aa3b, v250
	v_mul_f32_e32 v215, 0xbfb8aa3b, v251
	v_exp_f32_e32 v167, v167
	v_exp_f32_e32 v213, v213
	v_exp_f32_e32 v214, v214
	v_exp_f32_e32 v215, v215
	v_add_f32_e32 v167, 1.0, v167
	v_add_f32_e32 v213, 1.0, v213
	v_add_f32_e32 v214, 1.0, v214
	v_add_f32_e32 v215, 1.0, v215
	v_rcp_f32_e32 v167, v167
	v_rcp_f32_e32 v213, v213
	v_rcp_f32_e32 v214, v214
	v_rcp_f32_e32 v215, v215
	v_mul_f32_e32 v248, v248, v144
	v_mul_f32_e32 v249, v249, v145
	v_mul_f32_e32 v250, v250, v137
	v_mul_f32_e32 v251, v251, v166
	v_mul_f32_e32 v125, v248, v167
	v_mul_f32_e32 v109, v249, v213
	v_mul_f32_e32 v93, v250, v214
	v_mul_f32_e32 v77, v251, v215
	v_mov_b32_dpp v244, v94 row_shr:1 row_mask:0xf bank_mask:0xf
	v_mov_b32_dpp v245, v78 row_shr:1 row_mask:0xf bank_mask:0xf
	v_mov_b32_dpp v246, v86 row_shr:1 row_mask:0xf bank_mask:0xf
	v_mov_b32_dpp v247, v70 row_shr:1 row_mask:0xf bank_mask:0xf
	v_fma_f32 v248, v126, v210, v230
	v_fma_f32 v144, v118, v222, v238
	v_fma_f32 v249, v110, v210, v230
	v_fma_f32 v145, v102, v222, v238
	v_fma_f32 v250, v94, v210, v230
	v_fma_f32 v137, v86, v222, v238
	v_fma_f32 v251, v78, v210, v230
	v_fma_f32 v166, v70, v222, v238
	v_fmac_f32_e32 v248, v245, v194
	v_fmac_f32_e32 v144, v247, v202
	v_fmac_f32_e32 v249, v126, v194
	v_fmac_f32_e32 v145, v118, v202
	v_fmac_f32_e32 v250, v110, v194
	v_fmac_f32_e32 v137, v102, v202
	v_fmac_f32_e32 v251, v94, v194
	v_fmac_f32_e32 v166, v86, v202
	v_fmac_f32_e32 v248, v244, v178
	v_fmac_f32_e32 v144, v246, v186
	v_fmac_f32_e32 v249, v245, v178
	v_fmac_f32_e32 v145, v247, v186
	v_fmac_f32_e32 v250, v126, v178
	v_fmac_f32_e32 v137, v118, v186
	v_fmac_f32_e32 v251, v110, v178
	v_fmac_f32_e32 v166, v102, v186
	v_mul_f32_e32 v167, 0xbfb8aa3b, v248
	v_mul_f32_e32 v213, 0xbfb8aa3b, v249
	v_mul_f32_e32 v214, 0xbfb8aa3b, v250
	v_mul_f32_e32 v215, 0xbfb8aa3b, v251
	v_exp_f32_e32 v167, v167
	v_exp_f32_e32 v213, v213
	v_exp_f32_e32 v214, v214
	v_exp_f32_e32 v215, v215
	v_add_f32_e32 v167, 1.0, v167
	v_add_f32_e32 v213, 1.0, v213
	v_add_f32_e32 v214, 1.0, v214
	v_add_f32_e32 v215, 1.0, v215
	v_rcp_f32_e32 v167, v167
	v_rcp_f32_e32 v213, v213
	v_rcp_f32_e32 v214, v214
	v_rcp_f32_e32 v215, v215
	v_mul_f32_e32 v248, v248, v144
	v_mul_f32_e32 v249, v249, v145
	v_mul_f32_e32 v250, v250, v137
	v_mul_f32_e32 v251, v251, v166
	v_mul_f32_e32 v126, v248, v167
	v_mul_f32_e32 v110, v249, v213
	v_mul_f32_e32 v94, v250, v214
	v_mul_f32_e32 v78, v251, v215
	v_mov_b32_dpp v244, v95 row_shr:1 row_mask:0xf bank_mask:0xf
	v_mov_b32_dpp v245, v79 row_shr:1 row_mask:0xf bank_mask:0xf
	v_mov_b32_dpp v246, v87 row_shr:1 row_mask:0xf bank_mask:0xf
	v_mov_b32_dpp v247, v71 row_shr:1 row_mask:0xf bank_mask:0xf
; __device__ __forceinline__ float siluf_(float x) { return x * __builtin_amdgcn_rcpf(1.f + __expf(-x)); }
; template <int NT, bool SAMPLE>
; __device__ __forceinline__ void ffn_item(const bf16_t* U, int row0, bool has_hist, const float* st, int cgi, const float* w, const float* bias, bf16_t* ACT, float* state_out) {
;     ...
;     for (int t = 0; t < NT; ++t) {
;         float cg_[8], cv_[8], o[8];
;         unpack8(rg[t], cg_); unpack8(rv[t], cv_);
; #pragma unroll
;         for (int e = 0; e < 8; ++e) {
;             const float gg = g0[e] * wg[0][e] + g1[e] * wg[1][e] + cg_[e] * wg[2][e] + bg[e];
;             const float vv = v0[e] * wv[0][e] + v1[e] * wv[1][e] + cv_[e] * wv[2][e] + bvv[e];
;             o[e] = siluf_(gg) * vv; g0[e] = g1[e]; g1[e] = cg_[e]; v0[e] = v1[e]; v1[e] = cv_[e]; }
;         *(u32x4*)(ACT + (size_t)(row0 + t) * FF + c0) = pack8(o);
	v_fma_f32 v248, v127, v211, v231
	v_fma_f32 v144, v119, v223, v239
	v_fma_f32 v249, v111, v211, v231
	v_fma_f32 v145, v103, v223, v239
	v_fma_f32 v250, v95, v211, v231
	v_fma_f32 v137, v87, v223, v239
	v_fma_f32 v251, v79, v211, v231
	v_fma_f32 v166, v71, v223, v239
	v_fmac_f32_e32 v248, v245, v195
	v_fmac_f32_e32 v144, v247, v203
	v_fmac_f32_e32 v249, v127, v195
	v_fmac_f32_e32 v145, v119, v203
	v_fmac_f32_e32 v250, v111, v195
	v_fmac_f32_e32 v137, v103, v203
	v_fmac_f32_e32 v251, v95, v195
	v_fmac_f32_e32 v166, v87, v203
	v_fmac_f32_e32 v248, v244, v179
	v_fmac_f32_e32 v144, v246, v187
	v_fmac_f32_e32 v249, v245, v179
	v_fmac_f32_e32 v145, v247, v187
	v_fmac_f32_e32 v250, v127, v179
	v_fmac_f32_e32 v137, v119, v187
	v_fmac_f32_e32 v251, v111, v179
	v_fmac_f32_e32 v166, v103, v187
	v_mul_f32_e32 v167, 0xbfb8aa3b, v248
	v_mul_f32_e32 v213, 0xbfb8aa3b, v249
	v_mul_f32_e32 v214, 0xbfb8aa3b, v250
	v_mul_f32_e32 v215, 0xbfb8aa3b, v251
	v_exp_f32_e32 v167, v167
	v_exp_f32_e32 v213, v213
	v_exp_f32_e32 v214, v214
	v_exp_f32_e32 v215, v215
	v_add_f32_e32 v167, 1.0, v167
	v_add_f32_e32 v213, 1.0, v213
	v_add_f32_e32 v214, 1.0, v214
	v_add_f32_e32 v215, 1.0, v215
	v_rcp_f32_e32 v167, v167
	v_rcp_f32_e32 v213, v213
	v_rcp_f32_e32 v214, v214
	v_rcp_f32_e32 v215, v215
	v_mul_f32_e32 v248, v248, v144
	v_mul_f32_e32 v249, v249, v145
	v_mul_f32_e32 v250, v250, v137
	v_mul_f32_e32 v251, v251, v166
	v_mul_f32_e32 v127, v248, v167
	v_mul_f32_e32 v111, v249, v213
	v_mul_f32_e32 v95, v250, v214
	v_mul_f32_e32 v79, v251, v215
	v_mov_b32_dpp v244, v88 row_shr:1 row_mask:0xf bank_mask:0xf
	v_mov_b32_dpp v245, v72 row_shr:1 row_mask:0xf bank_mask:0xf
	v_mov_b32_dpp v246, v80 row_shr:1 row_mask:0xf bank_mask:0xf
	v_mov_b32_dpp v247, v64 row_shr:1 row_mask:0xf bank_mask:0xf
	v_fma_f32 v248, v120, v216, v232
	v_fma_f32 v144, v112, v224, v240
	v_fma_f32 v249, v104, v216, v232
	v_fma_f32 v145, v96, v224, v240
	v_fma_f32 v250, v88, v216, v232
	v_fma_f32 v137, v80, v224, v240
	v_fma_f32 v251, v72, v216, v232
	v_fma_f32 v166, v64, v224, v240
	v_fmac_f32_e32 v248, v245, v196
	v_fmac_f32_e32 v144, v247, v204
	v_fmac_f32_e32 v249, v120, v196
	v_fmac_f32_e32 v145, v112, v204
	v_fmac_f32_e32 v250, v104, v196
	v_fmac_f32_e32 v137, v96, v204
	v_fmac_f32_e32 v251, v88, v196
	v_fmac_f32_e32 v166, v80, v204
	v_fmac_f32_e32 v248, v244, v180
	v_fmac_f32_e32 v144, v246, v188
	v_fmac_f32_e32 v249, v245, v180
	v_fmac_f32_e32 v145, v247, v188
	v_fmac_f32_e32 v250, v120, v180
	v_fmac_f32_e32 v137, v112, v188
	v_fmac_f32_e32 v251, v104, v180
	v_fmac_f32_e32 v166, v96, v188
	v_mul_f32_e32 v167, 0xbfb8aa3b, v248
	v_mul_f32_e32 v213, 0xbfb8aa3b, v249
	v_mul_f32_e32 v214, 0xbfb8aa3b, v250
	v_mul_f32_e32 v215, 0xbfb8aa3b, v251
	v_exp_f32_e32 v167, v167
	v_exp_f32_e32 v213, v213
	v_exp_f32_e32 v214, v214
	v_exp_f32_e32 v215, v215
	v_add_f32_e32 v167, 1.0, v167
	v_add_f32_e32 v213, 1.0, v213
	v_add_f32_e32 v214, 1.0, v214
	v_add_f32_e32 v215, 1.0, v215
	v_rcp_f32_e32 v167, v167
	v_rcp_f32_e32 v213, v213
	v_rcp_f32_e32 v214, v214
	v_rcp_f32_e32 v215, v215
	v_mul_f32_e32 v248, v248, v144
	v_mul_f32_e32 v249, v249, v145
	v_mul_f32_e32 v250, v250, v137
	v_mul_f32_e32 v251, v251, v166
	v_mul_f32_e32 v120, v248, v167
	v_mul_f32_e32 v104, v249, v213
	v_mul_f32_e32 v88, v250, v214
	v_mul_f32_e32 v72, v251, v215
	v_mov_b32_dpp v244, v89 row_shr:1 row_mask:0xf bank_mask:0xf
	v_mov_b32_dpp v245, v73 row_shr:1 row_mask:0xf bank_mask:0xf
	v_mov_b32_dpp v246, v81 row_shr:1 row_mask:0xf bank_mask:0xf
	v_mov_b32_dpp v247, v65 row_shr:1 row_mask:0xf bank_mask:0xf
	v_fma_f32 v248, v121, v217, v233
	v_fma_f32 v144, v113, v225, v241
	v_fma_f32 v249, v105, v217, v233
	v_fma_f32 v145, v97, v225, v241
	v_fma_f32 v250, v89, v217, v233
	v_fma_f32 v137, v81, v225, v241
	v_fma_f32 v251, v73, v217, v233
	v_fma_f32 v166, v65, v225, v241
	v_fmac_f32_e32 v248, v245, v197
	v_fmac_f32_e32 v144, v247, v205
	v_fmac_f32_e32 v249, v121, v197
	v_fmac_f32_e32 v145, v113, v205
	v_fmac_f32_e32 v250, v105, v197
	v_fmac_f32_e32 v137, v97, v205
	v_fmac_f32_e32 v251, v89, v197
	v_fmac_f32_e32 v166, v81, v205
	v_fmac_f32_e32 v248, v244, v181
	v_fmac_f32_e32 v144, v246, v189
	v_fmac_f32_e32 v249, v245, v181
	v_fmac_f32_e32 v145, v247, v189
	v_fmac_f32_e32 v250, v121, v181
	v_fmac_f32_e32 v137, v113, v189
	v_fmac_f32_e32 v251, v105, v181
	v_fmac_f32_e32 v166, v97, v189
	v_mul_f32_e32 v167, 0xbfb8aa3b, v248
	v_mul_f32_e32 v213, 0xbfb8aa3b, v249
	v_mul_f32_e32 v214, 0xbfb8aa3b, v250
	v_mul_f32_e32 v215, 0xbfb8aa3b, v251
	v_exp_f32_e32 v167, v167
	v_exp_f32_e32 v213, v213
	v_exp_f32_e32 v214, v214
	v_exp_f32_e32 v215, v215
	v_add_f32_e32 v167, 1.0, v167
	v_add_f32_e32 v213, 1.0, v213
	v_add_f32_e32 v214, 1.0, v214
	v_add_f32_e32 v215, 1.0, v215
	v_rcp_f32_e32 v167, v167
	v_rcp_f32_e32 v213, v213
	v_rcp_f32_e32 v214, v214
	v_rcp_f32_e32 v215, v215
	v_mul_f32_e32 v248, v248, v144
	v_mul_f32_e32 v249, v249, v145
	v_mul_f32_e32 v250, v250, v137
	v_mul_f32_e32 v251, v251, v166
	v_mul_f32_e32 v121, v248, v167
	v_mul_f32_e32 v105, v249, v213
	v_mul_f32_e32 v89, v250, v214
	v_mul_f32_e32 v73, v251, v215
	v_mov_b32_dpp v244, v90 row_shr:1 row_mask:0xf bank_mask:0xf
	v_mov_b32_dpp v245, v74 row_shr:1 row_mask:0xf bank_mask:0xf
	v_mov_b32_dpp v246, v82 row_shr:1 row_mask:0xf bank_mask:0xf
	v_mov_b32_dpp v247, v66 row_shr:1 row_mask:0xf bank_mask:0xf
	v_fma_f32 v248, v122, v218, v234
	v_fma_f32 v144, v114, v226, v242
	v_fma_f32 v249, v106, v218, v234
	v_fma_f32 v145, v98, v226, v242
	v_fma_f32 v250, v90, v218, v234
	v_fma_f32 v137, v82, v226, v242
	v_fma_f32 v251, v74, v218, v234
	v_fma_f32 v166, v66, v226, v242
	v_fmac_f32_e32 v248, v245, v198
; __device__ __forceinline__ float siluf_(float x) { return x * __builtin_amdgcn_rcpf(1.f + __expf(-x)); }
; template <int NT, bool SAMPLE>
; __device__ __forceinline__ void ffn_item(const bf16_t* U, int row0, bool has_hist, const float* st, int cgi, const float* w, const float* bias, bf16_t* ACT, float* state_out) {
;     ...
;     for (int t = 0; t < NT; ++t) {
;         float cg_[8], cv_[8], o[8];
;         unpack8(rg[t], cg_); unpack8(rv[t], cv_);
; #pragma unroll
;         for (int e = 0; e < 8; ++e) {
;             const float gg = g0[e] * wg[0][e] + g1[e] * wg[1][e] + cg_[e] * wg[2][e] + bg[e];
;             const float vv = v0[e] * wv[0][e] + v1[e] * wv[1][e] + cv_[e] * wv[2][e] + bvv[e];
;             o[e] = siluf_(gg) * vv; g0[e] = g1[e]; g1[e] = cg_[e]; v0[e] = v1[e]; v1[e] = cv_[e]; }
;         *(u32x4*)(ACT + (size_t)(row0 + t) * FF + c0) = pack8(o);
	v_fmac_f32_e32 v144, v247, v206
	v_fmac_f32_e32 v249, v122, v198
	v_fmac_f32_e32 v145, v114, v206
	v_fmac_f32_e32 v250, v106, v198
	v_fmac_f32_e32 v137, v98, v206
	v_fmac_f32_e32 v251, v90, v198
	v_fmac_f32_e32 v166, v82, v206
	v_fmac_f32_e32 v248, v244, v182
	v_fmac_f32_e32 v144, v246, v190
	v_fmac_f32_e32 v249, v245, v182
	v_fmac_f32_e32 v145, v247, v190
	v_fmac_f32_e32 v250, v122, v182
	v_fmac_f32_e32 v137, v114, v190
	v_fmac_f32_e32 v251, v106, v182
	v_fmac_f32_e32 v166, v98, v190
	v_mul_f32_e32 v167, 0xbfb8aa3b, v248
	v_mul_f32_e32 v213, 0xbfb8aa3b, v249
	v_mul_f32_e32 v214, 0xbfb8aa3b, v250
	v_mul_f32_e32 v215, 0xbfb8aa3b, v251
	v_exp_f32_e32 v167, v167
	v_exp_f32_e32 v213, v213
	v_exp_f32_e32 v214, v214
	v_exp_f32_e32 v215, v215
	v_add_f32_e32 v167, 1.0, v167
	v_add_f32_e32 v213, 1.0, v213
	v_add_f32_e32 v214, 1.0, v214
	v_add_f32_e32 v215, 1.0, v215
	v_rcp_f32_e32 v167, v167
	v_rcp_f32_e32 v213, v213
	v_rcp_f32_e32 v214, v214
	v_rcp_f32_e32 v215, v215
	v_mul_f32_e32 v248, v248, v144
	v_mul_f32_e32 v249, v249, v145
	v_mul_f32_e32 v250, v250, v137
	v_mul_f32_e32 v251, v251, v166
	v_mul_f32_e32 v122, v248, v167
	v_mul_f32_e32 v106, v249, v213
	v_mul_f32_e32 v90, v250, v214
	v_mul_f32_e32 v74, v251, v215
	v_mov_b32_dpp v244, v91 row_shr:1 row_mask:0xf bank_mask:0xf
	v_mov_b32_dpp v245, v75 row_shr:1 row_mask:0xf bank_mask:0xf
	v_mov_b32_dpp v246, v83 row_shr:1 row_mask:0xf bank_mask:0xf
	v_mov_b32_dpp v247, v67 row_shr:1 row_mask:0xf bank_mask:0xf
	v_fma_f32 v248, v123, v219, v235
	v_fma_f32 v144, v115, v227, v243
	v_fma_f32 v249, v107, v219, v235
	v_fma_f32 v145, v99, v227, v243
	v_fma_f32 v250, v91, v219, v235
	v_fma_f32 v137, v83, v227, v243
	v_fma_f32 v251, v75, v219, v235
	v_fma_f32 v166, v67, v227, v243
	v_fmac_f32_e32 v248, v245, v199
	v_fmac_f32_e32 v144, v247, v207
	v_fmac_f32_e32 v249, v123, v199
	v_fmac_f32_e32 v145, v115, v207
	v_fmac_f32_e32 v250, v107, v199
	v_fmac_f32_e32 v137, v99, v207
	v_fmac_f32_e32 v251, v91, v199
	v_fmac_f32_e32 v166, v83, v207
	v_fmac_f32_e32 v248, v244, v183
	v_fmac_f32_e32 v144, v246, v191
	v_fmac_f32_e32 v249, v245, v183
	v_fmac_f32_e32 v145, v247, v191
	v_fmac_f32_e32 v250, v123, v183
	v_fmac_f32_e32 v137, v115, v191
	v_fmac_f32_e32 v251, v107, v183
	v_fmac_f32_e32 v166, v99, v191
	v_mul_f32_e32 v167, 0xbfb8aa3b, v248
	v_mul_f32_e32 v213, 0xbfb8aa3b, v249
	v_mul_f32_e32 v214, 0xbfb8aa3b, v250
	v_mul_f32_e32 v215, 0xbfb8aa3b, v251
	v_exp_f32_e32 v167, v167
	v_exp_f32_e32 v213, v213
	v_exp_f32_e32 v214, v214
	v_exp_f32_e32 v215, v215
	v_add_f32_e32 v167, 1.0, v167
	v_add_f32_e32 v213, 1.0, v213
	v_add_f32_e32 v214, 1.0, v214
	v_add_f32_e32 v215, 1.0, v215
	v_rcp_f32_e32 v167, v167
	v_rcp_f32_e32 v213, v213
	v_rcp_f32_e32 v214, v214
	v_rcp_f32_e32 v215, v215
	v_mul_f32_e32 v248, v248, v144
	v_mul_f32_e32 v249, v249, v145
	v_mul_f32_e32 v250, v250, v137
	v_mul_f32_e32 v251, v251, v166
	v_mul_f32_e32 v123, v248, v167
	v_mul_f32_e32 v107, v249, v213
	v_mul_f32_e32 v91, v250, v214
	v_mul_f32_e32 v75, v251, v215
	v_mov_b32_dpp v244, v28 row_shr:1 row_mask:0xf bank_mask:0xf
	v_mov_b32_dpp v245, v12 row_shr:1 row_mask:0xf bank_mask:0xf
	v_mov_b32_dpp v246, v20 row_shr:1 row_mask:0xf bank_mask:0xf
	v_mov_b32_dpp v247, v4 row_shr:1 row_mask:0xf bank_mask:0xf
	v_fma_f32 v248, v60, v208, v228
	v_fma_f32 v144, v52, v220, v236
	v_fma_f32 v249, v44, v208, v228
	v_fma_f32 v145, v36, v220, v236
	v_fma_f32 v250, v28, v208, v228
	v_fma_f32 v137, v20, v220, v236
	v_fma_f32 v251, v12, v208, v228
	v_fma_f32 v166, v4, v220, v236
	v_fmac_f32_e32 v248, v245, v192
	v_fmac_f32_e32 v144, v247, v200
	v_fmac_f32_e32 v249, v60, v192
	v_fmac_f32_e32 v145, v52, v200
	v_fmac_f32_e32 v250, v44, v192
	v_fmac_f32_e32 v137, v36, v200
	v_fmac_f32_e32 v251, v28, v192
	v_fmac_f32_e32 v166, v20, v200
	v_fmac_f32_e32 v248, v244, v176
	v_fmac_f32_e32 v144, v246, v184
	v_fmac_f32_e32 v249, v245, v176
	v_fmac_f32_e32 v145, v247, v184
	v_fmac_f32_e32 v250, v60, v176
	v_fmac_f32_e32 v137, v52, v184
	v_fmac_f32_e32 v251, v44, v176
	v_fmac_f32_e32 v166, v36, v184
	v_mul_f32_e32 v167, 0xbfb8aa3b, v248
	v_mul_f32_e32 v213, 0xbfb8aa3b, v249
	v_mul_f32_e32 v214, 0xbfb8aa3b, v250
	v_mul_f32_e32 v215, 0xbfb8aa3b, v251
	v_exp_f32_e32 v167, v167
	v_exp_f32_e32 v213, v213
	v_exp_f32_e32 v214, v214
	v_exp_f32_e32 v215, v215
	v_add_f32_e32 v167, 1.0, v167
	v_add_f32_e32 v213, 1.0, v213
	v_add_f32_e32 v214, 1.0, v214
	v_add_f32_e32 v215, 1.0, v215
	v_rcp_f32_e32 v167, v167
	v_rcp_f32_e32 v213, v213
	v_rcp_f32_e32 v214, v214
	v_rcp_f32_e32 v215, v215
	v_mul_f32_e32 v248, v248, v144
	v_mul_f32_e32 v249, v249, v145
	v_mul_f32_e32 v250, v250, v137
	v_mul_f32_e32 v251, v251, v166
	v_mul_f32_e32 v60, v248, v167
	v_mul_f32_e32 v44, v249, v213
	v_mul_f32_e32 v28, v250, v214
	v_mul_f32_e32 v12, v251, v215
	v_mov_b32_dpp v244, v29 row_shr:1 row_mask:0xf bank_mask:0xf
	v_mov_b32_dpp v245, v13 row_shr:1 row_mask:0xf bank_mask:0xf
	v_mov_b32_dpp v246, v21 row_shr:1 row_mask:0xf bank_mask:0xf
	v_mov_b32_dpp v247, v5 row_shr:1 row_mask:0xf bank_mask:0xf
	v_fma_f32 v248, v61, v209, v229
	v_fma_f32 v144, v53, v221, v237
	v_fma_f32 v249, v45, v209, v229
	v_fma_f32 v145, v37, v221, v237
	v_fma_f32 v250, v29, v209, v229
	v_fma_f32 v137, v21, v221, v237
	v_fma_f32 v251, v13, v209, v229
	v_fma_f32 v166, v5, v221, v237
	v_fmac_f32_e32 v248, v245, v193
	v_fmac_f32_e32 v144, v247, v201
	v_fmac_f32_e32 v249, v61, v193
	v_fmac_f32_e32 v145, v53, v201
	v_fmac_f32_e32 v250, v45, v193
	v_fmac_f32_e32 v137, v37, v201
	v_fmac_f32_e32 v251, v29, v193
	v_fmac_f32_e32 v166, v21, v201
	v_fmac_f32_e32 v248, v244, v177
	v_fmac_f32_e32 v144, v246, v185
	v_fmac_f32_e32 v249, v245, v177
; __device__ __forceinline__ float siluf_(float x) { return x * __builtin_amdgcn_rcpf(1.f + __expf(-x)); }
; template <int NT, bool SAMPLE>
; __device__ __forceinline__ void ffn_item(const bf16_t* U, int row0, bool has_hist, const float* st, int cgi, const float* w, const float* bias, bf16_t* ACT, float* state_out) {
;     ...
;     for (int t = 0; t < NT; ++t) {
;         float cg_[8], cv_[8], o[8];
;         unpack8(rg[t], cg_); unpack8(rv[t], cv_);
; #pragma unroll
;         for (int e = 0; e < 8; ++e) {
;             const float gg = g0[e] * wg[0][e] + g1[e] * wg[1][e] + cg_[e] * wg[2][e] + bg[e];
;             const float vv = v0[e] * wv[0][e] + v1[e] * wv[1][e] + cv_[e] * wv[2][e] + bvv[e];
;             o[e] = siluf_(gg) * vv; g0[e] = g1[e]; g1[e] = cg_[e]; v0[e] = v1[e]; v1[e] = cv_[e]; }
;         *(u32x4*)(ACT + (size_t)(row0 + t) * FF + c0) = pack8(o);
	v_fmac_f32_e32 v145, v247, v185
	v_fmac_f32_e32 v250, v61, v177
	v_fmac_f32_e32 v137, v53, v185
	v_fmac_f32_e32 v251, v45, v177
	v_fmac_f32_e32 v166, v37, v185
	v_mul_f32_e32 v167, 0xbfb8aa3b, v248
	v_mul_f32_e32 v213, 0xbfb8aa3b, v249
	v_mul_f32_e32 v214, 0xbfb8aa3b, v250
	v_mul_f32_e32 v215, 0xbfb8aa3b, v251
	v_exp_f32_e32 v167, v167
	v_exp_f32_e32 v213, v213
	v_exp_f32_e32 v214, v214
	v_exp_f32_e32 v215, v215
	v_add_f32_e32 v167, 1.0, v167
	v_add_f32_e32 v213, 1.0, v213
	v_add_f32_e32 v214, 1.0, v214
	v_add_f32_e32 v215, 1.0, v215
	v_rcp_f32_e32 v167, v167
	v_rcp_f32_e32 v213, v213
	v_rcp_f32_e32 v214, v214
	v_rcp_f32_e32 v215, v215
	v_mul_f32_e32 v248, v248, v144
	v_mul_f32_e32 v249, v249, v145
	v_mul_f32_e32 v250, v250, v137
	v_mul_f32_e32 v251, v251, v166
	v_mul_f32_e32 v61, v248, v167
	v_mul_f32_e32 v45, v249, v213
	v_mul_f32_e32 v29, v250, v214
	v_mul_f32_e32 v13, v251, v215
	v_mov_b32_dpp v244, v30 row_shr:1 row_mask:0xf bank_mask:0xf
	v_mov_b32_dpp v245, v14 row_shr:1 row_mask:0xf bank_mask:0xf
	v_mov_b32_dpp v246, v22 row_shr:1 row_mask:0xf bank_mask:0xf
	v_mov_b32_dpp v247, v6 row_shr:1 row_mask:0xf bank_mask:0xf
	v_fma_f32 v248, v62, v210, v230
	v_fma_f32 v144, v54, v222, v238
	v_fma_f32 v249, v46, v210, v230
	v_fma_f32 v145, v38, v222, v238
	v_fma_f32 v250, v30, v210, v230
	v_fma_f32 v137, v22, v222, v238
	v_fma_f32 v251, v14, v210, v230
	v_fma_f32 v166, v6, v222, v238
	v_fmac_f32_e32 v248, v245, v194
	v_fmac_f32_e32 v144, v247, v202
	v_fmac_f32_e32 v249, v62, v194
	v_fmac_f32_e32 v145, v54, v202
	v_fmac_f32_e32 v250, v46, v194
	v_fmac_f32_e32 v137, v38, v202
	v_fmac_f32_e32 v251, v30, v194
	v_fmac_f32_e32 v166, v22, v202
	v_fmac_f32_e32 v248, v244, v178
	v_fmac_f32_e32 v144, v246, v186
	v_fmac_f32_e32 v249, v245, v178
	v_fmac_f32_e32 v145, v247, v186
	v_fmac_f32_e32 v250, v62, v178
	v_fmac_f32_e32 v137, v54, v186
	v_fmac_f32_e32 v251, v46, v178
	v_fmac_f32_e32 v166, v38, v186
	v_mul_f32_e32 v167, 0xbfb8aa3b, v248
	v_mul_f32_e32 v213, 0xbfb8aa3b, v249
	v_mul_f32_e32 v214, 0xbfb8aa3b, v250
	v_mul_f32_e32 v215, 0xbfb8aa3b, v251
	v_exp_f32_e32 v167, v167
	v_exp_f32_e32 v213, v213
	v_exp_f32_e32 v214, v214
	v_exp_f32_e32 v215, v215
	v_add_f32_e32 v167, 1.0, v167
	v_add_f32_e32 v213, 1.0, v213
	v_add_f32_e32 v214, 1.0, v214
	v_add_f32_e32 v215, 1.0, v215
	v_rcp_f32_e32 v167, v167
	v_rcp_f32_e32 v213, v213
	v_rcp_f32_e32 v214, v214
	v_rcp_f32_e32 v215, v215
	v_mul_f32_e32 v248, v248, v144
	v_mul_f32_e32 v249, v249, v145
	v_mul_f32_e32 v250, v250, v137
	v_mul_f32_e32 v251, v251, v166
	v_mul_f32_e32 v62, v248, v167
	v_mul_f32_e32 v46, v249, v213
	v_mul_f32_e32 v30, v250, v214
	v_mul_f32_e32 v14, v251, v215
	v_mov_b32_dpp v244, v31 row_shr:1 row_mask:0xf bank_mask:0xf
	v_mov_b32_dpp v245, v15 row_shr:1 row_mask:0xf bank_mask:0xf
	v_mov_b32_dpp v246, v23 row_shr:1 row_mask:0xf bank_mask:0xf
	v_mov_b32_dpp v247, v7 row_shr:1 row_mask:0xf bank_mask:0xf
	v_fma_f32 v248, v63, v211, v231
	v_fma_f32 v144, v55, v223, v239
	v_fma_f32 v249, v47, v211, v231
	v_fma_f32 v145, v39, v223, v239
	v_fma_f32 v250, v31, v211, v231
	v_fma_f32 v137, v23, v223, v239
	v_fma_f32 v251, v15, v211, v231
	v_fma_f32 v166, v7, v223, v239
	v_fmac_f32_e32 v248, v245, v195
	v_fmac_f32_e32 v144, v247, v203
	v_fmac_f32_e32 v249, v63, v195
	v_fmac_f32_e32 v145, v55, v203
	v_fmac_f32_e32 v250, v47, v195
	v_fmac_f32_e32 v137, v39, v203
	v_fmac_f32_e32 v251, v31, v195
	v_fmac_f32_e32 v166, v23, v203
	v_fmac_f32_e32 v248, v244, v179
	v_fmac_f32_e32 v144, v246, v187
	v_fmac_f32_e32 v249, v245, v179
	v_fmac_f32_e32 v145, v247, v187
	v_fmac_f32_e32 v250, v63, v179
	v_fmac_f32_e32 v137, v55, v187
	v_fmac_f32_e32 v251, v47, v179
	v_fmac_f32_e32 v166, v39, v187
	v_mul_f32_e32 v167, 0xbfb8aa3b, v248
	v_mul_f32_e32 v213, 0xbfb8aa3b, v249
	v_mul_f32_e32 v214, 0xbfb8aa3b, v250
	v_mul_f32_e32 v215, 0xbfb8aa3b, v251
	v_exp_f32_e32 v167, v167
	v_exp_f32_e32 v213, v213
	v_exp_f32_e32 v214, v214
	v_exp_f32_e32 v215, v215
	v_add_f32_e32 v167, 1.0, v167
	v_add_f32_e32 v213, 1.0, v213
	v_add_f32_e32 v214, 1.0, v214
	v_add_f32_e32 v215, 1.0, v215
	v_rcp_f32_e32 v167, v167
	v_rcp_f32_e32 v213, v213
	v_rcp_f32_e32 v214, v214
	v_rcp_f32_e32 v215, v215
	v_mul_f32_e32 v248, v248, v144
	v_mul_f32_e32 v249, v249, v145
	v_mul_f32_e32 v250, v250, v137
	v_mul_f32_e32 v251, v251, v166
	v_mul_f32_e32 v63, v248, v167
	v_mul_f32_e32 v47, v249, v213
	v_mul_f32_e32 v31, v250, v214
	v_mul_f32_e32 v15, v251, v215
	v_mov_b32_dpp v244, v24 row_shr:1 row_mask:0xf bank_mask:0xf
	v_mov_b32_dpp v245, v8 row_shr:1 row_mask:0xf bank_mask:0xf
	v_mov_b32_dpp v246, v16 row_shr:1 row_mask:0xf bank_mask:0xf
	v_mov_b32_dpp v247, v0 row_shr:1 row_mask:0xf bank_mask:0xf
	v_fma_f32 v248, v56, v216, v232
	v_fma_f32 v144, v48, v224, v240
	v_fma_f32 v249, v40, v216, v232
	v_fma_f32 v145, v32, v224, v240
	v_fma_f32 v250, v24, v216, v232
	v_fma_f32 v137, v16, v224, v240
	v_fma_f32 v251, v8, v216, v232
	v_fma_f32 v166, v0, v224, v240
	v_fmac_f32_e32 v248, v245, v196
	v_fmac_f32_e32 v144, v247, v204
	v_fmac_f32_e32 v249, v56, v196
	v_fmac_f32_e32 v145, v48, v204
	v_fmac_f32_e32 v250, v40, v196
	v_fmac_f32_e32 v137, v32, v204
	v_fmac_f32_e32 v251, v24, v196
	v_fmac_f32_e32 v166, v16, v204
	v_fmac_f32_e32 v248, v244, v180
	v_fmac_f32_e32 v144, v246, v188
	v_fmac_f32_e32 v249, v245, v180
	v_fmac_f32_e32 v145, v247, v188
	v_fmac_f32_e32 v250, v56, v180
	v_fmac_f32_e32 v137, v48, v188
	v_fmac_f32_e32 v251, v40, v180
	v_fmac_f32_e32 v166, v32, v188
	v_mul_f32_e32 v167, 0xbfb8aa3b, v248
	v_mul_f32_e32 v213, 0xbfb8aa3b, v249
	v_mul_f32_e32 v214, 0xbfb8aa3b, v250
	v_mul_f32_e32 v215, 0xbfb8aa3b, v251
	v_exp_f32_e32 v167, v167
; __device__ __forceinline__ float siluf_(float x) { return x * __builtin_amdgcn_rcpf(1.f + __expf(-x)); }
; template <int NT, bool SAMPLE>
; __device__ __forceinline__ void ffn_item(const bf16_t* U, int row0, bool has_hist, const float* st, int cgi, const float* w, const float* bias, bf16_t* ACT, float* state_out) {
;     ...
;     for (int t = 0; t < NT; ++t) {
;         float cg_[8], cv_[8], o[8];
;         unpack8(rg[t], cg_); unpack8(rv[t], cv_);
; #pragma unroll
;         for (int e = 0; e < 8; ++e) {
;             const float gg = g0[e] * wg[0][e] + g1[e] * wg[1][e] + cg_[e] * wg[2][e] + bg[e];
;             const float vv = v0[e] * wv[0][e] + v1[e] * wv[1][e] + cv_[e] * wv[2][e] + bvv[e];
;             o[e] = siluf_(gg) * vv; g0[e] = g1[e]; g1[e] = cg_[e]; v0[e] = v1[e]; v1[e] = cv_[e]; }
;         *(u32x4*)(ACT + (size_t)(row0 + t) * FF + c0) = pack8(o);
	v_exp_f32_e32 v213, v213
	v_exp_f32_e32 v214, v214
	v_exp_f32_e32 v215, v215
	v_add_f32_e32 v167, 1.0, v167
	v_add_f32_e32 v213, 1.0, v213
	v_add_f32_e32 v214, 1.0, v214
	v_add_f32_e32 v215, 1.0, v215
	v_rcp_f32_e32 v167, v167
	v_rcp_f32_e32 v213, v213
	v_rcp_f32_e32 v214, v214
	v_rcp_f32_e32 v215, v215
	v_mul_f32_e32 v248, v248, v144
	v_mul_f32_e32 v249, v249, v145
	v_mul_f32_e32 v250, v250, v137
	v_mul_f32_e32 v251, v251, v166
	v_mul_f32_e32 v56, v248, v167
	v_mul_f32_e32 v40, v249, v213
	v_mul_f32_e32 v24, v250, v214
	v_mul_f32_e32 v8, v251, v215
	v_mov_b32_dpp v244, v25 row_shr:1 row_mask:0xf bank_mask:0xf
	v_mov_b32_dpp v245, v9 row_shr:1 row_mask:0xf bank_mask:0xf
	v_mov_b32_dpp v246, v17 row_shr:1 row_mask:0xf bank_mask:0xf
	v_mov_b32_dpp v247, v1 row_shr:1 row_mask:0xf bank_mask:0xf
	v_fma_f32 v248, v57, v217, v233
	v_fma_f32 v144, v49, v225, v241
	v_fma_f32 v249, v41, v217, v233
	v_fma_f32 v145, v33, v225, v241
	v_fma_f32 v250, v25, v217, v233
	v_fma_f32 v137, v17, v225, v241
	v_fma_f32 v251, v9, v217, v233
	v_fma_f32 v166, v1, v225, v241
	v_fmac_f32_e32 v248, v245, v197
	v_fmac_f32_e32 v144, v247, v205
	v_fmac_f32_e32 v249, v57, v197
	v_fmac_f32_e32 v145, v49, v205
	v_fmac_f32_e32 v250, v41, v197
	v_fmac_f32_e32 v137, v33, v205
	v_fmac_f32_e32 v251, v25, v197
	v_fmac_f32_e32 v166, v17, v205
	v_fmac_f32_e32 v248, v244, v181
	v_fmac_f32_e32 v144, v246, v189
	v_fmac_f32_e32 v249, v245, v181
	v_fmac_f32_e32 v145, v247, v189
	v_fmac_f32_e32 v250, v57, v181
	v_fmac_f32_e32 v137, v49, v189
	v_fmac_f32_e32 v251, v41, v181
	v_fmac_f32_e32 v166, v33, v189
	v_mul_f32_e32 v167, 0xbfb8aa3b, v248
	v_mul_f32_e32 v213, 0xbfb8aa3b, v249
	v_mul_f32_e32 v214, 0xbfb8aa3b, v250
	v_mul_f32_e32 v215, 0xbfb8aa3b, v251
	v_exp_f32_e32 v167, v167
	v_exp_f32_e32 v213, v213
	v_exp_f32_e32 v214, v214
	v_exp_f32_e32 v215, v215
	v_add_f32_e32 v167, 1.0, v167
	v_add_f32_e32 v213, 1.0, v213
	v_add_f32_e32 v214, 1.0, v214
	v_add_f32_e32 v215, 1.0, v215
	v_rcp_f32_e32 v167, v167
	v_rcp_f32_e32 v213, v213
	v_rcp_f32_e32 v214, v214
	v_rcp_f32_e32 v215, v215
	v_mul_f32_e32 v248, v248, v144
	v_mul_f32_e32 v249, v249, v145
	v_mul_f32_e32 v250, v250, v137
	v_mul_f32_e32 v251, v251, v166
	v_mul_f32_e32 v57, v248, v167
	v_mul_f32_e32 v41, v249, v213
	v_mul_f32_e32 v25, v250, v214
	v_mul_f32_e32 v9, v251, v215
	v_mov_b32_dpp v244, v26 row_shr:1 row_mask:0xf bank_mask:0xf
	v_mov_b32_dpp v245, v10 row_shr:1 row_mask:0xf bank_mask:0xf
	v_mov_b32_dpp v246, v18 row_shr:1 row_mask:0xf bank_mask:0xf
	v_mov_b32_dpp v247, v2 row_shr:1 row_mask:0xf bank_mask:0xf
	v_fma_f32 v248, v58, v218, v234
	v_fma_f32 v144, v50, v226, v242
	v_fma_f32 v249, v42, v218, v234
	v_fma_f32 v145, v34, v226, v242
	v_fma_f32 v250, v26, v218, v234
	v_fma_f32 v137, v18, v226, v242
	v_fma_f32 v251, v10, v218, v234
	v_fma_f32 v166, v2, v226, v242
	v_fmac_f32_e32 v248, v245, v198
	v_fmac_f32_e32 v144, v247, v206
	v_fmac_f32_e32 v249, v58, v198
	v_fmac_f32_e32 v145, v50, v206
	v_fmac_f32_e32 v250, v42, v198
	v_fmac_f32_e32 v137, v34, v206
	v_fmac_f32_e32 v251, v26, v198
	v_fmac_f32_e32 v166, v18, v206
	v_fmac_f32_e32 v248, v244, v182
	v_fmac_f32_e32 v144, v246, v190
	v_fmac_f32_e32 v249, v245, v182
	v_fmac_f32_e32 v145, v247, v190
	v_fmac_f32_e32 v250, v58, v182
	v_fmac_f32_e32 v137, v50, v190
	v_fmac_f32_e32 v251, v42, v182
	v_fmac_f32_e32 v166, v34, v190
	v_mul_f32_e32 v167, 0xbfb8aa3b, v248
	v_mul_f32_e32 v213, 0xbfb8aa3b, v249
	v_mul_f32_e32 v214, 0xbfb8aa3b, v250
	v_mul_f32_e32 v215, 0xbfb8aa3b, v251
	v_exp_f32_e32 v167, v167
	v_exp_f32_e32 v213, v213
	v_exp_f32_e32 v214, v214
	v_exp_f32_e32 v215, v215
	v_add_f32_e32 v167, 1.0, v167
	v_add_f32_e32 v213, 1.0, v213
	v_add_f32_e32 v214, 1.0, v214
	v_add_f32_e32 v215, 1.0, v215
	v_rcp_f32_e32 v167, v167
	v_rcp_f32_e32 v213, v213
	v_rcp_f32_e32 v214, v214
	v_rcp_f32_e32 v215, v215
	v_mul_f32_e32 v248, v248, v144
	v_mul_f32_e32 v249, v249, v145
; __device__ __forceinline__ float siluf_(float x) { return x * __builtin_amdgcn_rcpf(1.f + __expf(-x)); }
; template <int NT, bool SAMPLE>
; __device__ __forceinline__ void ffn_item(const bf16_t* U, int row0, bool has_hist, const float* st, int cgi, const float* w, const float* bias, bf16_t* ACT, float* state_out) {
;     ...
;         for (int e = 0; e < 8; ++e) {
;             const float gg = g0[e] * wg[0][e] + g1[e] * wg[1][e] + cg_[e] * wg[2][e] + bg[e];
;             const float vv = v0[e] * wv[0][e] + v1[e] * wv[1][e] + cv_[e] * wv[2][e] + bvv[e];
;             o[e] = siluf_(gg) * vv; g0[e] = g1[e]; g1[e] = cg_[e]; v0[e] = v1[e]; v1[e] = cv_[e]; }
;         *(u32x4*)(ACT + (size_t)(row0 + t) * FF + c0) = pack8(o);
	v_mul_f32_e32 v250, v250, v137
	v_mul_f32_e32 v251, v251, v166
	v_mul_f32_e32 v58, v248, v167
	v_mul_f32_e32 v42, v249, v213
	v_mul_f32_e32 v26, v250, v214
	v_mul_f32_e32 v10, v251, v215
	v_mov_b32_dpp v244, v27 row_shr:1 row_mask:0xf bank_mask:0xf
	v_mov_b32_dpp v245, v11 row_shr:1 row_mask:0xf bank_mask:0xf
	v_mov_b32_dpp v246, v19 row_shr:1 row_mask:0xf bank_mask:0xf
	v_mov_b32_dpp v247, v3 row_shr:1 row_mask:0xf bank_mask:0xf
	v_fma_f32 v248, v59, v219, v235
	v_fma_f32 v144, v51, v227, v243
	v_fma_f32 v249, v43, v219, v235
	v_fma_f32 v145, v35, v227, v243
	v_fma_f32 v250, v27, v219, v235
	v_fma_f32 v137, v19, v227, v243
	v_fma_f32 v251, v11, v219, v235
	v_fma_f32 v166, v3, v227, v243
	v_fmac_f32_e32 v248, v245, v199
	v_fmac_f32_e32 v144, v247, v207
	v_fmac_f32_e32 v249, v59, v199
	v_fmac_f32_e32 v145, v51, v207
	v_fmac_f32_e32 v250, v43, v199
	v_fmac_f32_e32 v137, v35, v207
	v_fmac_f32_e32 v251, v27, v199
	v_fmac_f32_e32 v166, v19, v207
	v_fmac_f32_e32 v248, v244, v183
	v_fmac_f32_e32 v144, v246, v191
	v_fmac_f32_e32 v249, v245, v183
	v_fmac_f32_e32 v145, v247, v191
	v_fmac_f32_e32 v250, v59, v183
	v_fmac_f32_e32 v137, v51, v191
	v_fmac_f32_e32 v251, v43, v183
	v_fmac_f32_e32 v166, v35, v191
	v_mul_f32_e32 v167, 0xbfb8aa3b, v248
	v_mul_f32_e32 v213, 0xbfb8aa3b, v249
	v_mul_f32_e32 v214, 0xbfb8aa3b, v250
	v_mul_f32_e32 v215, 0xbfb8aa3b, v251
	v_exp_f32_e32 v167, v167
	v_exp_f32_e32 v213, v213
	v_exp_f32_e32 v214, v214
	v_exp_f32_e32 v215, v215
	v_add_f32_e32 v167, 1.0, v167
	v_add_f32_e32 v213, 1.0, v213
	v_add_f32_e32 v214, 1.0, v214
	v_add_f32_e32 v215, 1.0, v215
	v_rcp_f32_e32 v167, v167
	v_rcp_f32_e32 v213, v213
	v_rcp_f32_e32 v214, v214
	v_rcp_f32_e32 v215, v215
	v_mul_f32_e32 v248, v248, v144
	v_mul_f32_e32 v249, v249, v145
	v_mul_f32_e32 v250, v250, v137
	v_mul_f32_e32 v251, v251, v166
	v_mul_f32_e32 v59, v248, v167
	v_mul_f32_e32 v43, v249, v213
	v_mul_f32_e32 v27, v250, v214
	v_mul_f32_e32 v11, v251, v215
	s_mov_b32 exec_lo, 0xfffcfffc
	s_mov_b32 exec_hi, 0xfffcfffc
	v_cvt_pk_bf16_f32 v168, v124, v125
	v_cvt_pk_bf16_f32 v169, v126, v127
	v_cvt_pk_bf16_f32 v170, v120, v121
	v_cvt_pk_bf16_f32 v171, v122, v123
	global_store_dwordx4 v136, v[168:171], s[14:15]
	s_add_u32 s14, s14, 0x2b00
	s_addc_u32 s15, s15, 0
	v_cvt_pk_bf16_f32 v172, v108, v109
	v_cvt_pk_bf16_f32 v173, v110, v111
	v_cvt_pk_bf16_f32 v174, v104, v105
	v_cvt_pk_bf16_f32 v175, v106, v107
	global_store_dwordx4 v136, v[172:175], s[14:15]
	s_add_u32 s14, s14, 0x2b00
	s_addc_u32 s15, s15, 0
	v_cvt_pk_bf16_f32 v168, v92, v93
	v_cvt_pk_bf16_f32 v169, v94, v95
	v_cvt_pk_bf16_f32 v170, v88, v89
	v_cvt_pk_bf16_f32 v171, v90, v91
	global_store_dwordx4 v136, v[168:171], s[14:15]
	s_add_u32 s14, s14, 0x2b00
	s_addc_u32 s15, s15, 0
	v_cvt_pk_bf16_f32 v172, v76, v77
	v_cvt_pk_bf16_f32 v173, v78, v79
	v_cvt_pk_bf16_f32 v174, v72, v73
	v_cvt_pk_bf16_f32 v175, v74, v75
	global_store_dwordx4 v136, v[172:175], s[14:15]
	s_add_u32 s14, s14, 0x14ff00
	s_addc_u32 s15, s15, 0
	v_cvt_pk_bf16_f32 v168, v60, v61
	v_cvt_pk_bf16_f32 v169, v62, v63
	v_cvt_pk_bf16_f32 v170, v56, v57
	v_cvt_pk_bf16_f32 v171, v58, v59
	global_store_dwordx4 v136, v[168:171], s[14:15]
	s_add_u32 s14, s14, 0x2b00
	s_addc_u32 s15, s15, 0
	v_cvt_pk_bf16_f32 v172, v44, v45
	v_cvt_pk_bf16_f32 v173, v46, v47
	v_cvt_pk_bf16_f32 v174, v40, v41
	v_cvt_pk_bf16_f32 v175, v42, v43
	global_store_dwordx4 v136, v[172:175], s[14:15]
	s_add_u32 s14, s14, 0x2b00
	s_addc_u32 s15, s15, 0
	v_cvt_pk_bf16_f32 v168, v28, v29
	v_cvt_pk_bf16_f32 v169, v30, v31
	v_cvt_pk_bf16_f32 v170, v24, v25
	v_cvt_pk_bf16_f32 v171, v26, v27
	global_store_dwordx4 v136, v[168:171], s[14:15]
	s_add_u32 s14, s14, 0x2b00
	s_addc_u32 s15, s15, 0
	v_cvt_pk_bf16_f32 v172, v12, v13
	v_cvt_pk_bf16_f32 v173, v14, v15
	v_cvt_pk_bf16_f32 v174, v8, v9
	v_cvt_pk_bf16_f32 v175, v10, v11
	global_store_dwordx4 v136, v[172:175], s[14:15]
	s_mov_b64 exec, -1
	s_branch .Lepi7_done

; #define LAS __attribute__((address_space(3)))
; __device__ __forceinline__ int ltid() { int t = threadIdx.x; asm volatile("" : "+v"(t)); return t; }
; __device__ __forceinline__ KArgs ka_get() { KArgs p = (KArgs)__builtin_amdgcn_kernarg_segment_ptr(); asm volatile("" : "+s"(p)); return p; }
; __global__ void __launch_bounds__(512, 2) mk_fwd(Args args) {
;     ...
;     if (IN(0)) { const KArgs KA = ka_get(); const int tid = ltid(), lane = tid & 63, wave = __builtin_amdgcn_readfirstlane(tid >> 6); (void)lane; (void)wave;
;         LAS float* scr = (LAS float*)(lds + wave * 16384);
;         const int gw = bx * 8 + wave, NGW = G * 8;
;         constexpr int I_IN = (DM / 64) * (9248 / 32), I_OUT = (DMIX / 64) * (DM / 32), I_UP = (DM / 64) * (FF2 / 32), I_DN = (FF / 64) * (DM / 32);
;         constexpr int n_items0 = I_IN + I_OUT + I_UP + I_DN;
;         for (int it = gw; it < n_items0; it += NGW) {
;             int r = it;
;             if (r < I_IN) { const int nblk = 9248 / 32, kb = r / nblk, nb = r % nblk; p0_transpose_item(w_in, DM, 9248, WinT, 64 * kb, 32 * nb, win_dest_row(32 * nb), scr, lane); continue; } r -= I_IN;
.LBB0_822:
	v_writelane_b32 v254, s3, 0
	v_writelane_b32 v254, s4, 1
	v_writelane_b32 v254, s8, 2
	v_writelane_b32 v254, s9, 3
	v_writelane_b32 v254, s10, 4
	v_writelane_b32 v254, s11, 5
	v_writelane_b32 v254, s12, 6
	v_writelane_b32 v254, s13, 7
	v_writelane_b32 v254, s14, 8
	v_writelane_b32 v254, s15, 9
	v_writelane_b32 v254, s16, 10
	v_writelane_b32 v254, s17, 11
	v_writelane_b32 v254, s18, 12
	v_writelane_b32 v254, s19, 13
	v_writelane_b32 v254, s20, 14
	v_writelane_b32 v254, s21, 15
	v_writelane_b32 v254, s22, 16
	v_writelane_b32 v254, s23, 17
	v_writelane_b32 v254, s24, 18
	v_writelane_b32 v254, s25, 19
	v_writelane_b32 v254, s26, 20
	v_writelane_b32 v254, s27, 21
	v_writelane_b32 v254, s28, 22
	v_writelane_b32 v254, s29, 23
	v_writelane_b32 v254, s30, 24
	v_writelane_b32 v254, s31, 25
	v_writelane_b32 v254, s32, 26
	v_writelane_b32 v254, s33, 27
	v_writelane_b32 v254, s34, 28
	v_writelane_b32 v254, s35, 29
	v_writelane_b32 v254, s36, 30
	v_writelane_b32 v254, s37, 31
	v_writelane_b32 v254, s38, 32
	v_writelane_b32 v254, s39, 33
	v_writelane_b32 v254, s40, 34
	v_writelane_b32 v254, s41, 35
	v_writelane_b32 v254, s42, 36
	v_writelane_b32 v254, s43, 37
	v_writelane_b32 v254, s44, 38
	v_writelane_b32 v254, s45, 39
	v_writelane_b32 v254, s46, 40
	v_writelane_b32 v254, s47, 41
	v_writelane_b32 v254, s48, 42
	v_writelane_b32 v254, s49, 43
	v_writelane_b32 v254, s50, 44
	v_writelane_b32 v254, s51, 45
	v_writelane_b32 v254, s52, 46
	v_writelane_b32 v254, s53, 47
	v_writelane_b32 v254, s54, 48
	v_writelane_b32 v254, s55, 49
	s_cmpk_lt_u32 s2, 182
	s_cbranch_scc1 .Ltdn_skip
	s_mov_b64 s[8:9], s[96:97]
	v_and_b32_e32 v3, 63, v212
	v_readfirstlane_b32 s4, v212
	s_sub_u32 s3, s2, 182
	s_lshl_b32 s3, s3, 3
	s_lshr_b32 s4, s4, 6
	s_add_u32 s3, s3, s4
	s_add_u32 s11, s3, 24352
	s_sub_u32 s10, s94, 182
	s_lshl_b32 s10, s10, 3
	s_cmpk_lt_u32 s11, 29856
	s_cbranch_scc0 .Ltdn_skip
	s_load_dwordx2 s[12:13], s[8:9], 0x38
	s_load_dwordx2 s[14:15], s[8:9], 0x90
	s_load_dwordx2 s[16:17], s[8:9], 0xa0
	s_load_dwordx2 s[18:19], s[8:9], 0xb8
	s_load_dwordx2 s[20:21], s[8:9], 0x98
	s_load_dwordx2 s[22:23], s[8:9], 0xd0
	v_lshrrev_b32_e32 v4, 3, v3
	v_and_b32_e32 v7, 7, v3
	v_lshlrev_b32_e32 v5, 4, v7
	v_lshlrev_b32_e32 v6, 5, v7
	s_lshl_b32 s24, s4, 14
	v_lshl_add_u32 v16, v4, 7, s24
	v_xor_b32_e32 v8, 0, v7
	v_lshl_add_u32 v8, v8, 4, v16
	v_xor_b32_e32 v9, 1, v7
	v_lshl_add_u32 v9, v9, 4, v16
	v_xor_b32_e32 v10, 2, v7
	v_lshl_add_u32 v10, v10, 4, v16
	v_xor_b32_e32 v11, 3, v7
	v_lshl_add_u32 v11, v11, 4, v16
	v_xor_b32_e32 v12, 4, v7
	v_lshl_add_u32 v12, v12, 4, v16
	v_xor_b32_e32 v13, 5, v7
	v_lshl_add_u32 v13, v13, 4, v16
	v_xor_b32_e32 v14, 6, v7
	v_lshl_add_u32 v14, v14, 4, v16
	v_xor_b32_e32 v15, 7, v7
	v_lshl_add_u32 v15, v15, 4, v16
	v_lshlrev_b32_e32 v20, 2, v7
	v_lshl_add_u32 v21, v7, 10, s24
	v_add_u32_e32 v16, 0, v4
	v_xor_b32_e32 v16, v16, v20
	v_lshl_add_u32 v16, v16, 2, v21
	v_add_u32_e32 v17, 8, v4
	v_xor_b32_e32 v17, v17, v20
	v_lshl_add_u32 v17, v17, 2, v21
	v_add_u32_e32 v18, 16, v4
	v_xor_b32_e32 v18, v18, v20
	v_lshl_add_u32 v18, v18, 2, v21
	v_add_u32_e32 v19, 24, v4
	v_xor_b32_e32 v19, v19, v20
	v_lshl_add_u32 v19, v19, 2, v21
	s_waitcnt lgkmcnt(0)
	s_mov_b32 s53, 0
	s_cmpk_lt_u32 s11, 9248
	s_cbranch_scc0 .Ltdn_pro0_notin
	s_mul_hi_u32 s40, s11, 14861479
	s_mul_i32 s42, s40, 289
	s_sub_u32 s41, s11, s42
	s_mul_i32 s42, s40, 2367488
	s_lshl_b32 s43, s41, 7
	s_add_u32 s42, s42, s43
	s_add_u32 s26, s12, s42
	s_addc_u32 s27, s13, 0
	s_mov_b32 s28, 36992
	s_lshl_b32 s45, s41, 5
	s_mov_b32 s46, s45
	s_cmpk_lt_u32 s45, 5120
	s_cbranch_scc1 .Ltdn_pro0_drow_done
	s_movk_i32 s46, 9216
	s_cmpk_lt_u32 s45, 5152
	s_cbranch_scc1 .Ltdn_pro0_drow_done
	s_sub_u32 s47, s45, 5152
	s_movk_i32 s43, 5120
	s_cmpk_lt_u32 s45, 7200
	s_cbranch_scc1 .Ltdn_pro0_drow_cf
	s_sub_u32 s47, s45, 7200
	s_movk_i32 s43, 5248

; #define LAS __attribute__((address_space(3)))
; __device__ __forceinline__ void p0_transpose_item(const float* W, int K, int N, bf16_t* WT, int k0, int n0, int drow0, LAS float* scr, int lane, const float* kscale = nullptr) {
;     const float ks = kscale ? kscale[k0 + lane] : 1.f;
; #pragma unroll 8
;     for (int i = 0; i < 32; ++i) { const int kk = 2 * i + (lane >> 5); scr[kk * 33 + (lane & 31)] = W[(size_t)(k0 + kk) * N + n0 + (lane & 31)] * __shfl(ks, kk); }
.Ltdn_pro0_decoded:
	v_mad_u32_u24 v20, v4, s28, v5
	s_lshl_b32 s29, s28, 3
	s_and_b32 s42, s40, 31
	s_lshl_b32 s42, s42, 8
	s_add_u32 s34, s20, s42
	s_addc_u32 s35, s21, 0
	global_load_dwordx4 v[32:35], v6, s[34:35]
	global_load_dwordx4 v[36:39], v6, s[34:35] offset:16
	global_load_dwordx4 v[40:43], v20, s[26:27] nt
	s_add_u32 s26, s26, s29
	s_addc_u32 s27, s27, 0
	global_load_dwordx4 v[44:47], v20, s[26:27] nt
	s_add_u32 s26, s26, s29
	s_addc_u32 s27, s27, 0
	global_load_dwordx4 v[48:51], v20, s[26:27] nt
	s_add_u32 s26, s26, s29
	s_addc_u32 s27, s27, 0
	global_load_dwordx4 v[52:55], v20, s[26:27] nt
	s_add_u32 s26, s26, s29
	s_addc_u32 s27, s27, 0
	global_load_dwordx4 v[56:59], v20, s[26:27] nt
	s_add_u32 s26, s26, s29
	s_addc_u32 s27, s27, 0
	global_load_dwordx4 v[60:63], v20, s[26:27] nt
	s_add_u32 s26, s26, s29
	s_addc_u32 s27, s27, 0
	global_load_dwordx4 v[64:67], v20, s[26:27] nt
	s_add_u32 s26, s26, s29
	s_addc_u32 s27, s27, 0
	global_load_dwordx4 v[68:71], v20, s[26:27] nt
	s_add_u32 s11, s11, s10
	s_cmpk_lt_u32 s11, 29856
	s_cbranch_scc0 .Ltdn_pro_single
	s_cmpk_lt_u32 s11, 9248
	s_cbranch_scc0 .Ltdn_pro1_notin
	s_mul_hi_u32 s40, s11, 14861479
	s_mul_i32 s42, s40, 289
	s_sub_u32 s41, s11, s42
	s_mul_i32 s42, s40, 2367488
	s_lshl_b32 s43, s41, 7
	s_add_u32 s42, s42, s43
	s_add_u32 s26, s12, s42
	s_addc_u32 s27, s13, 0
	s_mov_b32 s28, 36992
	s_lshl_b32 s45, s41, 5
	s_mov_b32 s46, s45
	s_cmpk_lt_u32 s45, 5120
	s_cbranch_scc1 .Ltdn_pro1_drow_done
	s_movk_i32 s46, 9216
	s_cmpk_lt_u32 s45, 5152
	s_cbranch_scc1 .Ltdn_pro1_drow_done
	s_sub_u32 s47, s45, 5152
	s_movk_i32 s43, 5120
	s_cmpk_lt_u32 s45, 7200
	s_cbranch_scc1 .Ltdn_pro1_drow_cf
	s_sub_u32 s47, s45, 7200
	s_movk_i32 s43, 5248

; __global__ void __launch_bounds__(512, 2) mk_fwd(Args args) {
;     ...
;         for (int it = gw; it < n_items0; it += NGW) {
;             int r = it;
;             if (r < I_IN) { const int nblk = 9248 / 32, kb = r / nblk, nb = r % nblk; p0_transpose_item(w_in, DM, 9248, WinT, 64 * kb, 32 * nb, win_dest_row(32 * nb), scr, lane); continue; } r -= I_IN;
.Ltdn_body0:
	s_mov_b32 s54, 0
	s_cmp_eq_u32 s53, 0
	s_cbranch_scc1 .Ltdn_noload0
	s_cmpk_lt_u32 s11, 29856
	s_cbranch_scc0 .Ltdn_noload0
	s_cmpk_lt_u32 s11, 9248
	s_cbranch_scc0 .Ltdn_m0_notin
	s_mul_hi_u32 s40, s11, 14861479
	s_mul_i32 s42, s40, 289
	s_sub_u32 s41, s11, s42
	s_mul_i32 s42, s40, 2367488
	s_lshl_b32 s43, s41, 7
	s_add_u32 s42, s42, s43
	s_add_u32 s26, s12, s42
	s_addc_u32 s27, s13, 0
	s_mov_b32 s28, 36992
	s_lshl_b32 s45, s41, 5
	s_mov_b32 s46, s45
	s_cmpk_lt_u32 s45, 5120
	s_cbranch_scc1 .Ltdn_m0_drow_done
	s_movk_i32 s46, 9216
	s_cmpk_lt_u32 s45, 5152
	s_cbranch_scc1 .Ltdn_m0_drow_done
	s_sub_u32 s47, s45, 5152
	s_movk_i32 s43, 5120
	s_cmpk_lt_u32 s45, 7200
	s_cbranch_scc1 .Ltdn_m0_drow_cf
	s_sub_u32 s47, s45, 7200
	s_movk_i32 s43, 5248

; #define SEAM(k) do { if (IN(k) && IN((k) + 1)) xcd_barrier(gbar); } while (0)
; __device__ __forceinline__ void xcd_barrier(const XcdBarrier& b) {
;     asm volatile("s_waitcnt vmcnt(0)" ::: "memory");
;     __syncthreads();
;     if (threadIdx.x == 0) {
;         unsigned* bar = b.bar;
;         __builtin_amdgcn_s_waitcnt(0);
;         unsigned nloc = b.st[0], nx = b.st[1];
;         if (nloc == 0u) { xcd_barrier_complete(bar, b.x, nloc, nx); b.st[0] = nloc; b.st[1] = nx; }
; __global__ void __launch_bounds__(512, 2) mk_fwd(Args args) {
;     ...
;     SEAM(0);
.Ltdn_done:
.Ltdn_skip:
	v_readlane_b32 s3, v254, 0
	v_readlane_b32 s4, v254, 1
	v_readlane_b32 s8, v254, 2
	v_readlane_b32 s9, v254, 3
	v_readlane_b32 s10, v254, 4
	v_readlane_b32 s11, v254, 5
	v_readlane_b32 s12, v254, 6
	v_readlane_b32 s13, v254, 7
	v_readlane_b32 s14, v254, 8
	v_readlane_b32 s15, v254, 9
	v_readlane_b32 s16, v254, 10
	v_readlane_b32 s17, v254, 11
	v_readlane_b32 s18, v254, 12
	v_readlane_b32 s19, v254, 13
	v_readlane_b32 s20, v254, 14
	v_readlane_b32 s21, v254, 15
	v_readlane_b32 s22, v254, 16
	v_readlane_b32 s23, v254, 17
	v_readlane_b32 s24, v254, 18
	v_readlane_b32 s25, v254, 19
	v_readlane_b32 s26, v254, 20
	v_readlane_b32 s27, v254, 21
	v_readlane_b32 s28, v254, 22
	v_readlane_b32 s29, v254, 23
	v_readlane_b32 s30, v254, 24
	v_readlane_b32 s31, v254, 25
	v_readlane_b32 s32, v254, 26
	v_readlane_b32 s33, v254, 27
	v_readlane_b32 s34, v254, 28
	v_readlane_b32 s35, v254, 29
	v_readlane_b32 s36, v254, 30
	v_readlane_b32 s37, v254, 31
	v_readlane_b32 s38, v254, 32
	v_readlane_b32 s39, v254, 33
	v_readlane_b32 s40, v254, 34
	v_readlane_b32 s41, v254, 35
	v_readlane_b32 s42, v254, 36
	v_readlane_b32 s43, v254, 37
	v_readlane_b32 s44, v254, 38
	v_readlane_b32 s45, v254, 39
	v_readlane_b32 s46, v254, 40
	v_readlane_b32 s47, v254, 41
	v_readlane_b32 s48, v254, 42
	v_readlane_b32 s49, v254, 43
	v_readlane_b32 s50, v254, 44
	v_readlane_b32 s51, v254, 45
	v_readlane_b32 s52, v254, 46
	v_readlane_b32 s53, v254, 47
	v_readlane_b32 s54, v254, 48
	v_readlane_b32 s55, v254, 49
	s_nop 4
	s_cmp_gt_i32 s89, 8
	s_waitcnt lgkmcnt(0)
	s_cselect_b64 s[4:5], -1, 0
	s_and_b64 s[0:1], s[0:1], s[4:5]
	s_andn2_b64 vcc, exec, s[0:1]
	s_cbranch_vccnz .LBB0_876
	s_waitcnt vmcnt(0)
	s_waitcnt vmcnt(0)
	s_barrier
	s_and_saveexec_b64 s[0:1], s[90:91]
	s_cbranch_execz .LBB0_875
	s_add_i32 s3, 0, 0x23fc0
	v_mov_b32_e32 v0, s3
	s_waitcnt vmcnt(0) expcnt(0) lgkmcnt(0)
	ds_read_b32 v2, v0
	s_add_i32 s3, 0, 0x23fc4
	v_mov_b32_e32 v0, s3
	ds_read_b32 v0, v0
	s_waitcnt lgkmcnt(1)
	v_cmp_ne_u32_e32 vcc, 0, v2
	s_cbranch_vccnz .LBB0_839
	v_readlane_b32 s6, v253, 0
	v_readlane_b32 s7, v253, 1
	s_load_dwordx2 s[10:11], s[6:7], 0x4
	s_add_u32 s6, s74, 0x1000
	s_addc_u32 s7, s75, 0
	s_add_u32 s8, s74, 0x1100
	s_addc_u32 s9, s75, 0
	s_waitcnt lgkmcnt(0)
	s_mul_i32 s3, s10, s94
	s_add_u32 s10, s74, 0x1200
	s_mul_i32 s3, s3, s11
	s_addc_u32 s11, s75, 0
	s_add_u32 s12, s74, 0x1300
	s_addc_u32 s13, s75, 0
	s_mov_b32 s20, 1
	v_mov_b32_e32 v16, 0
	s_branch .LBB0_827
